# rg_phase<false> items: the bank-conflicted gate-result LDS stores issued as soon as their data is final instead of bunched before the barrier
# speedup vs baseline: 1.0014x; 1.0014x over previous
.LBB0_281:
	v_mov_b32_e32 v0, v204
	s_nop 0
	v_and_b32_e32 v3, 0xffff0000, v40
	v_lshlrev_b32_e32 v2, 3, v0
	v_and_b32_e32 v116, 56, v2
	v_lshlrev_b32_e32 v2, 16, v40
	v_pk_fma_f32 v[2:3], v[32:33], v[2:3], v[48:49]
	v_lshlrev_b32_e32 v108, 16, v24
	v_and_b32_e32 v109, 0xffff0000, v24
	v_pk_fma_f32 v[2:3], v[8:9], v[108:109], v[2:3]
	v_lshlrev_b32_e32 v108, 16, v52
	v_and_b32_e32 v109, 0xffff0000, v52
	v_pk_fma_f32 v[2:3], v[12:13], v[108:109], v[2:3]
	v_lshlrev_b32_e32 v108, 16, v56
	v_and_b32_e32 v109, 0xffff0000, v56
	v_pk_fma_f32 v[108:109], v[16:17], v[108:109], v[2:3]
	v_lshlrev_b32_e32 v2, 16, v42
	v_and_b32_e32 v3, 0xffff0000, v42
	v_pk_fma_f32 v[2:3], v[28:29], v[2:3], v[44:45]
	v_lshlrev_b32_e32 v110, 16, v26
	v_and_b32_e32 v111, 0xffff0000, v26
	v_pk_fma_f32 v[2:3], v[4:5], v[110:111], v[2:3]
	v_lshlrev_b32_e32 v110, 16, v54
	v_and_b32_e32 v111, 0xffff0000, v54
	v_pk_fma_f32 v[2:3], v[20:21], v[110:111], v[2:3]
	v_lshlrev_b32_e32 v110, 16, v58
	v_and_b32_e32 v111, 0xffff0000, v58
	v_pk_fma_f32 v[112:113], v[36:37], v[110:111], v[2:3]
	v_lshlrev_b32_e32 v2, 16, v41
	v_and_b32_e32 v3, 0xffff0000, v41
	v_pk_fma_f32 v[2:3], v[34:35], v[2:3], v[50:51]
	v_lshlrev_b32_e32 v110, 16, v25
	v_and_b32_e32 v111, 0xffff0000, v25
	v_pk_fma_f32 v[2:3], v[10:11], v[110:111], v[2:3]
	v_lshlrev_b32_e32 v110, 16, v53
	v_and_b32_e32 v111, 0xffff0000, v53
	v_pk_fma_f32 v[2:3], v[14:15], v[110:111], v[2:3]
	v_lshlrev_b32_e32 v110, 16, v57
	v_and_b32_e32 v111, 0xffff0000, v57
	v_pk_fma_f32 v[110:111], v[18:19], v[110:111], v[2:3]
	v_lshlrev_b32_e32 v2, 16, v43
	v_and_b32_e32 v3, 0xffff0000, v43
	v_pk_fma_f32 v[2:3], v[30:31], v[2:3], v[46:47]
	v_lshlrev_b32_e32 v114, 16, v27
	v_and_b32_e32 v115, 0xffff0000, v27
	v_pk_fma_f32 v[2:3], v[6:7], v[114:115], v[2:3]
	v_lshlrev_b32_e32 v114, 16, v55
	v_and_b32_e32 v115, 0xffff0000, v55
	v_pk_fma_f32 v[2:3], v[22:23], v[114:115], v[2:3]
	v_lshlrev_b32_e32 v114, 16, v59
	v_and_b32_e32 v115, 0xffff0000, v59
	v_pk_fma_f32 v[114:115], v[38:39], v[114:115], v[2:3]
	v_ashrrev_i32_e32 v3, 3, v0
	v_lshl_add_u32 v117, v3, 8, 0
	v_lshl_add_u32 v118, v116, 2, v117
	ds_write_b128 v118, v[108:111]
	ds_write_b128 v118, v[112:115] offset:16
	v_cvt_pk_bf16_f32 v108, v108, v109
	v_cvt_pk_bf16_f32 v109, v110, v111
	v_cvt_pk_bf16_f32 v110, v112, v113
	v_mul_lo_u32 v3, v3, s67
	v_lshlrev_b32_e32 v112, 1, v116
	v_and_b32_e32 v127, 15, v0
	v_cvt_pk_bf16_f32 v111, v114, v115
	v_add3_u32 v3, v117, v3, v112
	v_and_b32_e32 v2, 48, v0
	ds_write_b128 v3, v[108:111] offset:16384
	v_mul_u32_u24_e32 v3, 0x90, v127
	v_add3_u32 v3, 0, v2, v3
	s_waitcnt lgkmcnt(0)
	s_barrier
	ds_read_b128 v[108:111], v3 offset:16384
	ds_read_b128 v[112:115], v3 offset:16448
	ds_read_b128 v[120:123], v3 offset:18688
	ds_read_b128 v[128:131], v3 offset:18752
	s_waitcnt lgkmcnt(1)
	v_mfma_f32_16x16x32_bf16 v[132:135], v[60:63], v[120:123], 0
	s_add_i32 s2, 0, 0xe400
	v_cmp_gt_u32_e32 vcc, s45, v0
	v_lshlrev_b32_e32 v127, 8, v127
	v_mfma_f32_16x16x32_bf16 v[136:139], v[76:79], v[120:123], 0
	ds_read_b128 v[120:123], v3 offset:20992
	ds_read_b128 v[140:143], v3 offset:21056
	v_mfma_f32_16x16x32_bf16 v[116:119], v[60:63], v[108:111], 0
	v_mfma_f32_16x16x32_bf16 v[108:111], v[76:79], v[108:111], 0
	s_waitcnt lgkmcnt(1)
	v_mfma_f32_16x16x32_bf16 v[144:147], v[60:63], v[120:123], 0
	v_mfma_f32_16x16x32_bf16 v[148:151], v[76:79], v[120:123], 0
	ds_read_b128 v[120:123], v3 offset:23296
	ds_read_b128 v[154:157], v3 offset:23360
	v_mov_b32_e32 v3, s2
	v_mfma_f32_16x16x32_bf16 v[166:169], v[64:67], v[112:115], v[116:119]
	s_waitcnt lgkmcnt(1)
	v_mfma_f32_16x16x32_bf16 v[158:161], v[60:63], v[120:123], 0
	v_mfma_f32_16x16x32_bf16 v[162:165], v[76:79], v[120:123], 0
	v_mfma_f32_16x16x32_bf16 v[120:123], v[80:83], v[112:115], v[108:111]
	v_mfma_f32_16x16x32_bf16 v[132:135], v[64:67], v[128:131], v[132:135]
	v_mfma_f32_16x16x32_bf16 v[116:119], v[80:83], v[128:131], v[136:139]
	s_nop 5
	v_add_f32_e32 v122, v90, v122
	v_mul_f32_e32 v122, 0xbfb8aa3b, v122
	v_exp_f32_e32 v122, v122
	v_mfma_f32_16x16x32_bf16 v[128:131], v[64:67], v[140:143], v[144:147]
	v_add_f32_e32 v123, v91, v123
	v_mul_f32_e32 v123, 0xbfb8aa3b, v123
	v_exp_f32_e32 v123, v123
	v_mfma_f32_16x16x32_bf16 v[112:115], v[80:83], v[140:143], v[148:151]
	v_mov_b32_e32 v140, s73
	v_cndmask_b32_e32 v3, v3, v140, vcc
	v_lshlrev_b32_e32 v140, 7, v0
	v_and_b32_e32 v140, 0x4000, v140
	v_add3_u32 v3, v3, v140, v127
	v_add_f32_e32 v140, v84, v166
	v_mul_f32_e32 v140, 0xbfb8aa3b, v140
	v_add_f32_e32 v141, v85, v167
	v_exp_f32_e32 v140, v140
	v_mul_f32_e32 v141, 0xbfb8aa3b, v141
	v_exp_f32_e32 v141, v141
	v_lshlrev_b32_e32 v127, 1, v0
	v_and_b32_e32 v127, 0x80, v127
	v_add_f32_e32 v140, 1.0, v140
	v_rcp_f32_e32 v140, v140
	v_add3_u32 v2, v3, v127, v2
	v_add_f32_e32 v3, 1.0, v141
	v_add_f32_e32 v141, v86, v168
	v_mul_f32_e32 v141, 0xbfb8aa3b, v141
	v_rcp_f32_e32 v3, v3
	v_exp_f32_e32 v141, v141
	v_add_f32_e32 v142, v87, v169
	v_mul_f32_e32 v142, 0xbfb8aa3b, v142
	v_mul_f32_e32 v127, 0xc1000000, v140
	v_exp_f32_e32 v142, v142
	v_mul_f32_e32 v127, v92, v127
	v_cndmask_b32_e32 v140, v140, v127, vcc
	v_mul_f32_e32 v127, 0xc1000000, v3
	v_add_f32_e32 v141, 1.0, v141
	v_mul_f32_e32 v127, v93, v127
	v_rcp_f32_e32 v143, v141
	v_cndmask_b32_e32 v141, v3, v127, vcc
	v_add_f32_e32 v3, 1.0, v142
	v_rcp_f32_e32 v3, v3
	v_mul_f32_e32 v127, 0xc1000000, v143
	v_mul_f32_e32 v127, v94, v127
	v_cndmask_b32_e32 v142, v143, v127, vcc
	v_mul_f32_e32 v127, 0xc1000000, v3
	v_mul_f32_e32 v127, v95, v127
	v_cndmask_b32_e32 v143, v3, v127, vcc
	v_add_f32_e32 v3, v84, v132
	v_mul_f32_e32 v3, 0xbfb8aa3b, v3
	v_exp_f32_e32 v3, v3
	v_add_f32_e32 v127, v85, v133
	v_mul_f32_e32 v127, 0xbfb8aa3b, v127
	v_exp_f32_e32 v127, v127
	v_add_f32_e32 v3, 1.0, v3
	v_rcp_f32_e32 v3, v3
	v_add_f32_e32 v133, v86, v134
	v_add_f32_e32 v127, 1.0, v127
	v_mul_f32_e32 v133, 0xbfb8aa3b, v133
	v_rcp_f32_e32 v127, v127
	v_exp_f32_e32 v133, v133
	v_add_f32_e32 v134, v87, v135
	v_mul_f32_e32 v134, 0xbfb8aa3b, v134
	v_mul_f32_e32 v132, 0xc1000000, v3
	v_exp_f32_e32 v134, v134
	v_mul_f32_e32 v132, v92, v132
	v_cndmask_b32_e32 v132, v3, v132, vcc
	v_mul_f32_e32 v3, 0xc1000000, v127
	v_add_f32_e32 v133, 1.0, v133
	v_mul_f32_e32 v3, v93, v3
	v_rcp_f32_e32 v135, v133
	v_cndmask_b32_e32 v133, v127, v3, vcc
	v_add_f32_e32 v3, 1.0, v134
	v_rcp_f32_e32 v3, v3
	v_mul_f32_e32 v127, 0xc1000000, v135
	v_mul_f32_e32 v127, v94, v127
	v_cndmask_b32_e32 v134, v135, v127, vcc
	v_mul_f32_e32 v127, 0xc1000000, v3
	v_mul_f32_e32 v127, v95, v127
	v_cndmask_b32_e32 v135, v3, v127, vcc
	v_add_f32_e32 v3, v84, v128
	v_mul_f32_e32 v3, 0xbfb8aa3b, v3
	v_exp_f32_e32 v3, v3
	v_add_f32_e32 v127, v85, v129
	v_mul_f32_e32 v127, 0xbfb8aa3b, v127
	v_exp_f32_e32 v127, v127
	v_add_f32_e32 v3, 1.0, v3
	v_rcp_f32_e32 v3, v3
	v_add_f32_e32 v129, v86, v130
	v_add_f32_e32 v127, 1.0, v127
	v_mul_f32_e32 v129, 0xbfb8aa3b, v129
	v_rcp_f32_e32 v127, v127
	v_exp_f32_e32 v129, v129
	v_add_f32_e32 v130, v87, v131
	v_mul_f32_e32 v130, 0xbfb8aa3b, v130
	v_mul_f32_e32 v128, 0xc1000000, v3
	v_exp_f32_e32 v130, v130
	v_mul_f32_e32 v128, v92, v128
	v_cndmask_b32_e32 v128, v3, v128, vcc
	v_mul_f32_e32 v3, 0xc1000000, v127
	v_add_f32_e32 v129, 1.0, v129
	v_mul_f32_e32 v3, v93, v3
	v_rcp_f32_e32 v131, v129
	v_cndmask_b32_e32 v129, v127, v3, vcc
	v_add_f32_e32 v3, 1.0, v130
	v_rcp_f32_e32 v3, v3
	s_waitcnt lgkmcnt(0)
	v_mfma_f32_16x16x32_bf16 v[136:139], v[64:67], v[154:157], v[158:161]
	ds_write_b128 v2, v[140:143]
	ds_write_b128 v2, v[132:135] offset:4096
	v_mul_f32_e32 v127, 0xc1000000, v131
	v_mul_f32_e32 v127, v94, v127
	v_cndmask_b32_e32 v130, v131, v127, vcc
	v_mul_f32_e32 v127, 0xc1000000, v3
	v_mul_f32_e32 v127, v95, v127
	v_cndmask_b32_e32 v131, v3, v127, vcc
	s_nop 1
	v_add_f32_e32 v3, v84, v136
	v_mul_f32_e32 v3, 0xbfb8aa3b, v3
	v_exp_f32_e32 v3, v3
	v_add_f32_e32 v127, v85, v137
	v_mul_f32_e32 v127, 0xbfb8aa3b, v127
	v_exp_f32_e32 v127, v127
	v_add_f32_e32 v3, 1.0, v3
	v_rcp_f32_e32 v3, v3
	ds_write_b128 v2, v[128:131] offset:8192
	v_add_f32_e32 v129, v86, v138
	v_add_f32_e32 v127, 1.0, v127
	v_mul_f32_e32 v129, 0xbfb8aa3b, v129
	v_rcp_f32_e32 v127, v127
	v_exp_f32_e32 v129, v129
	v_add_f32_e32 v130, v87, v139
	v_mul_f32_e32 v130, 0xbfb8aa3b, v130
	v_mul_f32_e32 v128, 0xc1000000, v3
	v_exp_f32_e32 v130, v130
	v_mul_f32_e32 v128, v92, v128
	v_cndmask_b32_e32 v128, v3, v128, vcc
	v_mul_f32_e32 v3, 0xc1000000, v127
	v_add_f32_e32 v129, 1.0, v129
	v_mul_f32_e32 v3, v93, v3
	v_rcp_f32_e32 v131, v129
	v_cndmask_b32_e32 v129, v127, v3, vcc
	v_add_f32_e32 v3, 1.0, v130
	v_rcp_f32_e32 v3, v3
	v_mul_f32_e32 v127, 0xc1000000, v131
	v_mul_f32_e32 v127, v94, v127
	v_cndmask_b32_e32 v130, v131, v127, vcc
	v_mul_f32_e32 v127, 0xc1000000, v3
	v_mul_f32_e32 v127, v95, v127
	v_cndmask_b32_e32 v131, v3, v127, vcc
	v_add_f32_e32 v3, v88, v120
	ds_write_b128 v2, v[128:131] offset:12288
	v_mul_f32_e32 v3, 0xbfb8aa3b, v3
	v_exp_f32_e32 v3, v3
	v_add_f32_e32 v120, v89, v121
	v_mul_f32_e32 v120, 0xbfb8aa3b, v120
	v_exp_f32_e32 v120, v120
	v_add_f32_e32 v3, 1.0, v3
	v_rcp_f32_e32 v3, v3
	v_add_f32_e32 v122, 1.0, v122
	v_add_f32_e32 v120, 1.0, v120
	v_rcp_f32_e32 v121, v120
	v_mul_f32_e32 v120, 0xc1000000, v3
	v_mul_f32_e32 v120, v96, v120
	v_cndmask_b32_e32 v120, v3, v120, vcc
	v_mul_f32_e32 v3, 0xc1000000, v121
	v_mul_f32_e32 v3, v97, v3
	v_rcp_f32_e32 v122, v122
	v_cndmask_b32_e32 v121, v121, v3, vcc
	v_add_f32_e32 v3, 1.0, v123
	v_rcp_f32_e32 v3, v3
	v_mul_f32_e32 v123, 0xc1000000, v122
	v_mul_f32_e32 v123, v98, v123
	v_cndmask_b32_e32 v122, v122, v123, vcc
	v_mul_f32_e32 v123, 0xc1000000, v3
	v_mul_f32_e32 v123, v99, v123
	v_cndmask_b32_e32 v123, v3, v123, vcc
	v_add_f32_e32 v3, v88, v116
	ds_write_b128 v2, v[120:123] offset:64
	v_mul_f32_e32 v3, 0xbfb8aa3b, v3
	v_exp_f32_e32 v3, v3
	v_add_f32_e32 v116, v89, v117
	v_mul_f32_e32 v116, 0xbfb8aa3b, v116
	v_exp_f32_e32 v116, v116
	v_add_f32_e32 v3, 1.0, v3
	v_rcp_f32_e32 v3, v3
	v_add_f32_e32 v118, v90, v118
	v_add_f32_e32 v116, 1.0, v116
	v_mul_f32_e32 v118, 0xbfb8aa3b, v118
	v_rcp_f32_e32 v117, v116
	v_exp_f32_e32 v118, v118
	v_add_f32_e32 v119, v91, v119
	v_mul_f32_e32 v119, 0xbfb8aa3b, v119
	v_mul_f32_e32 v116, 0xc1000000, v3
	v_exp_f32_e32 v119, v119
	v_mul_f32_e32 v116, v96, v116
	v_cndmask_b32_e32 v116, v3, v116, vcc
	v_mul_f32_e32 v3, 0xc1000000, v117
	v_add_f32_e32 v118, 1.0, v118
	v_mul_f32_e32 v3, v97, v3
	v_rcp_f32_e32 v118, v118
	v_cndmask_b32_e32 v117, v117, v3, vcc
	v_add_f32_e32 v3, 1.0, v119
	v_rcp_f32_e32 v3, v3
	v_mul_f32_e32 v119, 0xc1000000, v118
	v_mul_f32_e32 v119, v98, v119
	v_cndmask_b32_e32 v118, v118, v119, vcc
	v_mul_f32_e32 v119, 0xc1000000, v3
	v_mul_f32_e32 v119, v99, v119
	v_cndmask_b32_e32 v119, v3, v119, vcc
	v_add_f32_e32 v3, v88, v112
	ds_write_b128 v2, v[116:119] offset:4160
	v_mul_f32_e32 v3, 0xbfb8aa3b, v3
	v_exp_f32_e32 v3, v3
	v_add_f32_e32 v112, v89, v113
	v_mul_f32_e32 v112, 0xbfb8aa3b, v112
	v_exp_f32_e32 v112, v112
	v_add_f32_e32 v3, 1.0, v3
	v_rcp_f32_e32 v3, v3
	v_add_f32_e32 v114, v90, v114
	v_add_f32_e32 v112, 1.0, v112
	v_mul_f32_e32 v114, 0xbfb8aa3b, v114
	v_rcp_f32_e32 v113, v112
	v_exp_f32_e32 v114, v114
	v_add_f32_e32 v115, v91, v115
	v_mul_f32_e32 v115, 0xbfb8aa3b, v115
	v_mul_f32_e32 v112, 0xc1000000, v3
	v_exp_f32_e32 v115, v115
	v_mul_f32_e32 v112, v96, v112
	v_cndmask_b32_e32 v112, v3, v112, vcc
	v_mul_f32_e32 v3, 0xc1000000, v113
	v_add_f32_e32 v114, 1.0, v114
	v_mul_f32_e32 v3, v97, v3
	v_rcp_f32_e32 v114, v114
	v_cndmask_b32_e32 v113, v113, v3, vcc
	v_add_f32_e32 v3, 1.0, v115
	v_rcp_f32_e32 v3, v3
	v_mfma_f32_16x16x32_bf16 v[108:111], v[80:83], v[154:157], v[162:165]
	v_mul_f32_e32 v115, 0xc1000000, v114
	v_mul_f32_e32 v115, v98, v115
	v_cndmask_b32_e32 v114, v114, v115, vcc
	v_mul_f32_e32 v115, 0xc1000000, v3
	v_mul_f32_e32 v115, v99, v115
	v_cndmask_b32_e32 v115, v3, v115, vcc
	s_nop 1
	ds_write_b128 v2, v[112:115] offset:8256
	v_add_f32_e32 v3, v88, v108
	v_mul_f32_e32 v3, 0xbfb8aa3b, v3
	v_exp_f32_e32 v3, v3
	v_add_f32_e32 v108, v89, v109
	v_mul_f32_e32 v108, 0xbfb8aa3b, v108
	v_exp_f32_e32 v108, v108
	v_add_f32_e32 v3, 1.0, v3
	v_rcp_f32_e32 v3, v3
	v_add_f32_e32 v110, v90, v110
	v_add_f32_e32 v108, 1.0, v108
	v_mul_f32_e32 v110, 0xbfb8aa3b, v110
	v_rcp_f32_e32 v109, v108
	v_exp_f32_e32 v110, v110
	v_add_f32_e32 v111, v91, v111
	v_mul_f32_e32 v111, 0xbfb8aa3b, v111
	v_mul_f32_e32 v108, 0xc1000000, v3
	v_exp_f32_e32 v111, v111
	v_mul_f32_e32 v108, v96, v108
	v_cndmask_b32_e32 v108, v3, v108, vcc
	v_mul_f32_e32 v3, 0xc1000000, v109
	v_add_f32_e32 v110, 1.0, v110
	v_mul_f32_e32 v3, v97, v3
	v_rcp_f32_e32 v110, v110
	v_cndmask_b32_e32 v109, v109, v3, vcc
	v_add_f32_e32 v3, 1.0, v111
	v_rcp_f32_e32 v3, v3
	v_mul_f32_e32 v111, 0xc1000000, v110
	v_mul_f32_e32 v111, v98, v111
	v_cndmask_b32_e32 v110, v110, v111, vcc
	v_mul_f32_e32 v111, 0xc1000000, v3
	v_mul_f32_e32 v111, v99, v111
	v_cndmask_b32_e32 v111, v3, v111, vcc
	ds_write_b128 v2, v[108:111] offset:12352
	v_lshlrev_b32_e32 v3, 2, v0
	v_lshlrev_b32_e32 v108, 4, v0


	v_and_b32_e32 v2, 60, v3
	v_and_b32_e32 v109, 0xffffc000, v108
	v_lshlrev_b32_e32 v2, 2, v2
	v_add_u32_e32 v109, 0, v109
	v_and_b32_e32 v108, 0x3f00, v108
	v_add3_u32 v128, v109, v108, v2
	s_waitcnt lgkmcnt(0)
	s_barrier
	ds_read_b128 v[120:123], v128 offset:25600
	ds_read_b128 v[112:115], v128 offset:58368
	v_add_u32_e32 v127, 0, v2
	v_add_u32_e32 v129, v127, v108
	ds_read_b128 v[116:119], v129
	s_waitcnt lgkmcnt(2)
	v_mul_f32_e32 v108, 0x3fb8aa3b, v120
	v_exp_f32_e32 v108, v108
	v_add_f32_e32 v109, v120, v120
	v_cmp_nlt_f32_e32 vcc, s75, v109
	s_and_saveexec_b64 s[8:9], vcc
	s_xor_b64 s[8:9], exec, s[8:9]
	v_fma_f32 v120, -v108, v108, 1.0
	s_andn2_saveexec_b64 s[8:9], s[8:9]
	v_fmamk_f32 v110, v109, 0x3c088889, v125
	v_fmaak_f32 v110, v109, v110, 0x3e2aaaab
	v_fma_f32 v110, v109, v110, 0.5
	v_fma_f32 v110, v109, v110, 1.0
	v_mul_f32_e64 v120, v110, -v109
	s_or_b64 exec, exec, s[8:9]
	v_mul_f32_e32 v109, 0x3fb8aa3b, v121
	v_exp_f32_e32 v109, v109
	v_add_f32_e32 v110, v121, v121
	v_cmp_nlt_f32_e32 vcc, s75, v110
	s_and_saveexec_b64 s[8:9], vcc
	s_xor_b64 s[8:9], exec, s[8:9]
	v_fma_f32 v121, -v109, v109, 1.0
	s_andn2_saveexec_b64 s[8:9], s[8:9]
	v_fmamk_f32 v111, v110, 0x3c088889, v125
	v_fmaak_f32 v111, v110, v111, 0x3e2aaaab
	v_fma_f32 v111, v110, v111, 0.5
	v_fma_f32 v111, v110, v111, 1.0
	v_mul_f32_e64 v121, v111, -v110
	s_or_b64 exec, exec, s[8:9]
	v_mul_f32_e32 v110, 0x3fb8aa3b, v122
	v_exp_f32_e32 v110, v110
	v_add_f32_e32 v111, v122, v122
	v_cmp_nlt_f32_e32 vcc, s75, v111
	s_and_saveexec_b64 s[8:9], vcc
	s_xor_b64 s[8:9], exec, s[8:9]
	v_fma_f32 v122, -v110, v110, 1.0
	s_andn2_saveexec_b64 s[8:9], s[8:9]
	v_fmamk_f32 v122, v111, 0x3c088889, v125
	v_fmaak_f32 v122, v111, v122, 0x3e2aaaab
	v_fma_f32 v122, v111, v122, 0.5
	v_fma_f32 v122, v111, v122, 1.0
	v_mul_f32_e64 v122, v122, -v111
	s_or_b64 exec, exec, s[8:9]
	v_mul_f32_e32 v111, 0x3fb8aa3b, v123
	v_exp_f32_e32 v111, v111
	v_add_f32_e32 v130, v123, v123
	v_cmp_nlt_f32_e32 vcc, s75, v130
	s_and_saveexec_b64 s[8:9], vcc
	s_xor_b64 s[8:9], exec, s[8:9]
	v_fma_f32 v123, -v111, v111, 1.0
	s_andn2_saveexec_b64 s[8:9], s[8:9]
	v_fmamk_f32 v123, v130, 0x3c088889, v125
	v_fmaak_f32 v123, v130, v123, 0x3e2aaaab
	v_fma_f32 v123, v130, v123, 0.5
	v_fma_f32 v123, v130, v123, 1.0
	v_mul_f32_e64 v123, v123, -v130
	s_or_b64 exec, exec, s[8:9]
	v_max_f32_e32 v120, v120, v120
	v_max_f32_e32 v120, 0, v120
	v_sqrt_f32_e32 v120, v120
	v_max_f32_e32 v121, v121, v121
	v_max_f32_e32 v121, 0, v121
	v_sqrt_f32_e32 v121, v121
	s_waitcnt lgkmcnt(1)
	v_mul_f32_e32 v112, v112, v120
	s_waitcnt lgkmcnt(0)
	v_mul_f32_e32 v112, v116, v112
	v_max_f32_e32 v116, v122, v122
	v_max_f32_e32 v120, v123, v123
	v_max_f32_e32 v116, 0, v116
	v_max_f32_e32 v120, 0, v120
	v_sqrt_f32_e32 v116, v116
	v_sqrt_f32_e32 v120, v120
	v_mul_f32_e32 v113, v113, v121
	v_mul_f32_e32 v113, v117, v113
	v_mul_f32_e32 v114, v114, v116
	v_mul_f32_e32 v115, v115, v120
	v_mul_f32_e32 v114, v118, v114
	v_mul_f32_e32 v115, v119, v115
	ds_write_b128 v128, v[108:111] offset:25600
	ds_write_b128 v128, v[112:115] offset:58368
	v_add_u32_e32 v108, 0x800, v3
	v_and_b32_e32 v109, 0x3ffff000, v108
	v_and_b32_e32 v108, 0xfc0, v108
	v_lshl_add_u32 v109, v109, 2, 0
	v_lshlrev_b32_e32 v108, 2, v108
	v_add3_u32 v130, v109, v108, v2
	ds_read_b128 v[120:123], v130 offset:25600
	ds_read_b128 v[112:115], v130 offset:58368
	v_add_u32_e32 v108, v127, v108
	ds_read_b128 v[116:119], v108
	s_waitcnt lgkmcnt(2)
	v_mul_f32_e32 v108, 0x3fb8aa3b, v120
	v_exp_f32_e32 v108, v108
	v_add_f32_e32 v109, v120, v120
	v_cmp_nlt_f32_e32 vcc, s75, v109
	s_and_saveexec_b64 s[8:9], vcc
	s_xor_b64 s[8:9], exec, s[8:9]
	v_fma_f32 v120, -v108, v108, 1.0
	s_andn2_saveexec_b64 s[8:9], s[8:9]
	v_fmamk_f32 v110, v109, 0x3c088889, v125
	v_fmaak_f32 v110, v109, v110, 0x3e2aaaab
	v_fma_f32 v110, v109, v110, 0.5
	v_fma_f32 v110, v109, v110, 1.0
	v_mul_f32_e64 v120, v110, -v109
	s_or_b64 exec, exec, s[8:9]
	v_mul_f32_e32 v109, 0x3fb8aa3b, v121
	v_exp_f32_e32 v109, v109
	v_add_f32_e32 v110, v121, v121
	v_cmp_nlt_f32_e32 vcc, s75, v110
	s_and_saveexec_b64 s[8:9], vcc
	s_xor_b64 s[8:9], exec, s[8:9]
	v_fma_f32 v121, -v109, v109, 1.0
	s_andn2_saveexec_b64 s[8:9], s[8:9]
	v_fmamk_f32 v111, v110, 0x3c088889, v125
	v_fmaak_f32 v111, v110, v111, 0x3e2aaaab
	v_fma_f32 v111, v110, v111, 0.5
	v_fma_f32 v111, v110, v111, 1.0
	v_mul_f32_e64 v121, v111, -v110
	s_or_b64 exec, exec, s[8:9]
	v_mul_f32_e32 v110, 0x3fb8aa3b, v122
	v_exp_f32_e32 v110, v110
	v_add_f32_e32 v111, v122, v122
	v_cmp_nlt_f32_e32 vcc, s75, v111
	s_and_saveexec_b64 s[8:9], vcc
	s_xor_b64 s[8:9], exec, s[8:9]
	v_fma_f32 v122, -v110, v110, 1.0
	s_andn2_saveexec_b64 s[8:9], s[8:9]
	v_fmamk_f32 v122, v111, 0x3c088889, v125
	v_fmaak_f32 v122, v111, v122, 0x3e2aaaab
	v_fma_f32 v122, v111, v122, 0.5
	v_fma_f32 v122, v111, v122, 1.0
	v_mul_f32_e64 v122, v122, -v111
	s_or_b64 exec, exec, s[8:9]
	v_mul_f32_e32 v111, 0x3fb8aa3b, v123
	v_exp_f32_e32 v111, v111
	v_add_f32_e32 v131, v123, v123
	v_cmp_nlt_f32_e32 vcc, s75, v131
	s_and_saveexec_b64 s[8:9], vcc
	s_xor_b64 s[8:9], exec, s[8:9]
	v_fma_f32 v123, -v111, v111, 1.0
	s_andn2_saveexec_b64 s[8:9], s[8:9]
	v_fmamk_f32 v123, v131, 0x3c088889, v125
	v_fmaak_f32 v123, v131, v123, 0x3e2aaaab
	v_fma_f32 v123, v131, v123, 0.5
	v_fma_f32 v123, v131, v123, 1.0
	v_mul_f32_e64 v123, v123, -v131
	s_or_b64 exec, exec, s[8:9]
	v_max_f32_e32 v120, v120, v120
	v_max_f32_e32 v120, 0, v120
	v_sqrt_f32_e32 v120, v120
	v_max_f32_e32 v121, v121, v121
	v_max_f32_e32 v121, 0, v121
	v_sqrt_f32_e32 v121, v121
	s_waitcnt lgkmcnt(1)
	v_mul_f32_e32 v112, v112, v120
	s_waitcnt lgkmcnt(0)
	v_mul_f32_e32 v112, v116, v112
	v_max_f32_e32 v116, v122, v122
	v_max_f32_e32 v120, v123, v123
	v_max_f32_e32 v116, 0, v116
	v_max_f32_e32 v120, 0, v120
	v_sqrt_f32_e32 v116, v116
	v_sqrt_f32_e32 v120, v120
	v_mul_f32_e32 v113, v113, v121
	v_mul_f32_e32 v113, v117, v113
	v_mul_f32_e32 v114, v114, v116
	v_mul_f32_e32 v115, v115, v120
	v_mul_f32_e32 v114, v118, v114
	v_mul_f32_e32 v115, v119, v115
	ds_write_b128 v130, v[108:111] offset:25600
	ds_write_b128 v130, v[112:115] offset:58368
	ds_read_b128 v[120:123], v128 offset:41984
	v_add_u32_e32 v130, 0xe400, v128
	ds_read_b128 v[112:115], v130 offset:16384
	ds_read_b128 v[116:119], v129
	s_waitcnt lgkmcnt(2)
	v_mul_f32_e32 v108, 0x3fb8aa3b, v120
	v_exp_f32_e32 v108, v108
	v_add_f32_e32 v109, v120, v120
	v_cmp_nlt_f32_e32 vcc, s75, v109
	s_and_saveexec_b64 s[8:9], vcc
	s_xor_b64 s[8:9], exec, s[8:9]
	v_fma_f32 v120, -v108, v108, 1.0
	s_andn2_saveexec_b64 s[8:9], s[8:9]
	v_fmamk_f32 v110, v109, 0x3c088889, v125
	v_fmaak_f32 v110, v109, v110, 0x3e2aaaab
	v_fma_f32 v110, v109, v110, 0.5
	v_fma_f32 v110, v109, v110, 1.0
	v_mul_f32_e64 v120, v110, -v109
	s_or_b64 exec, exec, s[8:9]
	v_mul_f32_e32 v109, 0x3fb8aa3b, v121
	v_exp_f32_e32 v109, v109
	v_add_f32_e32 v110, v121, v121
	v_cmp_nlt_f32_e32 vcc, s75, v110
	s_and_saveexec_b64 s[8:9], vcc
	s_xor_b64 s[8:9], exec, s[8:9]
	v_fma_f32 v121, -v109, v109, 1.0
	s_andn2_saveexec_b64 s[8:9], s[8:9]
	v_fmamk_f32 v111, v110, 0x3c088889, v125
	v_fmaak_f32 v111, v110, v111, 0x3e2aaaab
	v_fma_f32 v111, v110, v111, 0.5
	v_fma_f32 v111, v110, v111, 1.0
	v_mul_f32_e64 v121, v111, -v110
	s_or_b64 exec, exec, s[8:9]
	v_mul_f32_e32 v110, 0x3fb8aa3b, v122
	v_exp_f32_e32 v110, v110
	v_add_f32_e32 v111, v122, v122
	v_cmp_nlt_f32_e32 vcc, s75, v111
	s_and_saveexec_b64 s[8:9], vcc
	s_xor_b64 s[8:9], exec, s[8:9]
	v_fma_f32 v122, -v110, v110, 1.0
	s_andn2_saveexec_b64 s[8:9], s[8:9]
	v_fmamk_f32 v122, v111, 0x3c088889, v125
	v_fmaak_f32 v122, v111, v122, 0x3e2aaaab
	v_fma_f32 v122, v111, v122, 0.5
	v_fma_f32 v122, v111, v122, 1.0
	v_mul_f32_e64 v122, v122, -v111
	s_or_b64 exec, exec, s[8:9]
	v_mul_f32_e32 v111, 0x3fb8aa3b, v123
	v_exp_f32_e32 v111, v111
	v_add_f32_e32 v129, v123, v123
	v_cmp_nlt_f32_e32 vcc, s75, v129
	s_and_saveexec_b64 s[8:9], vcc
	s_xor_b64 s[8:9], exec, s[8:9]
	v_fma_f32 v123, -v111, v111, 1.0
	s_andn2_saveexec_b64 s[8:9], s[8:9]
	v_fmamk_f32 v123, v129, 0x3c088889, v125
	v_fmaak_f32 v123, v129, v123, 0x3e2aaaab
	v_fma_f32 v123, v129, v123, 0.5
	v_fma_f32 v123, v129, v123, 1.0
	v_mul_f32_e64 v123, v123, -v129
	s_or_b64 exec, exec, s[8:9]
	v_max_f32_e32 v120, v120, v120
	v_max_f32_e32 v120, 0, v120
	v_sqrt_f32_e32 v120, v120
	v_max_f32_e32 v121, v121, v121
	v_max_f32_e32 v121, 0, v121
	v_sqrt_f32_e32 v121, v121
	s_waitcnt lgkmcnt(1)
	v_mul_f32_e32 v112, v112, v120
	s_waitcnt lgkmcnt(0)
	v_mul_f32_e32 v112, v116, v112
	v_max_f32_e32 v116, v122, v122
	v_max_f32_e32 v120, v123, v123
	v_max_f32_e32 v116, 0, v116
	v_max_f32_e32 v120, 0, v120
	v_sqrt_f32_e32 v116, v116
	v_sqrt_f32_e32 v120, v120
	v_mul_f32_e32 v113, v113, v121
	v_add_u32_e32 v3, 0x1800, v3
	v_mul_f32_e32 v114, v114, v116
	v_mul_f32_e32 v115, v115, v120
	v_mul_f32_e32 v113, v117, v113
	v_mul_f32_e32 v114, v118, v114
	v_mul_f32_e32 v115, v119, v115
	ds_write_b128 v128, v[108:111] offset:41984
	ds_write_b128 v130, v[112:115] offset:16384
	v_and_b32_e32 v108, 0x3ffff000, v3
	v_and_b32_e32 v3, 0xfc0, v3
	v_lshl_add_u32 v108, v108, 2, 0
	v_lshlrev_b32_e32 v3, 2, v3
	v_add3_u32 v2, v108, v3, v2
	ds_read_b128 v[120:123], v2 offset:25600
	ds_read_b128 v[112:115], v2 offset:58368
	v_add_u32_e32 v3, v127, v3
	ds_read_b128 v[116:119], v3
	s_waitcnt lgkmcnt(2)
	v_mul_f32_e32 v3, 0x3fb8aa3b, v120
	v_exp_f32_e32 v108, v3
	v_add_f32_e32 v109, v120, v120
	v_cmp_nlt_f32_e32 vcc, s75, v109
	s_and_saveexec_b64 s[8:9], vcc
	s_xor_b64 s[8:9], exec, s[8:9]
	v_fma_f32 v3, -v108, v108, 1.0
	s_andn2_saveexec_b64 s[8:9], s[8:9]
	v_fmamk_f32 v3, v109, 0x3c088889, v125
	v_fmaak_f32 v3, v109, v3, 0x3e2aaaab
	v_fma_f32 v3, v109, v3, 0.5
	v_fma_f32 v3, v109, v3, 1.0
	v_mul_f32_e64 v3, v3, -v109
	s_or_b64 exec, exec, s[8:9]
	v_mul_f32_e32 v109, 0x3fb8aa3b, v121
	v_exp_f32_e32 v109, v109
	v_add_f32_e32 v110, v121, v121
	v_cmp_nlt_f32_e32 vcc, s75, v110
	s_and_saveexec_b64 s[8:9], vcc
	s_xor_b64 s[8:9], exec, s[8:9]
	v_fma_f32 v121, -v109, v109, 1.0
	s_andn2_saveexec_b64 s[8:9], s[8:9]
	v_fmamk_f32 v111, v110, 0x3c088889, v125
	v_fmaak_f32 v111, v110, v111, 0x3e2aaaab
	v_fma_f32 v111, v110, v111, 0.5
	v_fma_f32 v111, v110, v111, 1.0
	v_mul_f32_e64 v121, v111, -v110
	s_or_b64 exec, exec, s[8:9]
	v_mul_f32_e32 v110, 0x3fb8aa3b, v122
	v_exp_f32_e32 v110, v110
	v_add_f32_e32 v111, v122, v122
	v_cmp_nlt_f32_e32 vcc, s75, v111
	s_and_saveexec_b64 s[8:9], vcc
	s_xor_b64 s[8:9], exec, s[8:9]
	v_fma_f32 v122, -v110, v110, 1.0
	s_andn2_saveexec_b64 s[8:9], s[8:9]
	v_fmamk_f32 v120, v111, 0x3c088889, v125
	v_fmaak_f32 v120, v111, v120, 0x3e2aaaab
	v_fma_f32 v120, v111, v120, 0.5
	v_fma_f32 v120, v111, v120, 1.0
	v_mul_f32_e64 v122, v120, -v111
	s_or_b64 exec, exec, s[8:9]
	v_mul_f32_e32 v111, 0x3fb8aa3b, v123
	v_exp_f32_e32 v111, v111
	v_add_f32_e32 v120, v123, v123
	v_cmp_nlt_f32_e32 vcc, s75, v120
	s_and_saveexec_b64 s[8:9], vcc
	s_xor_b64 s[8:9], exec, s[8:9]
	v_fma_f32 v123, -v111, v111, 1.0
	s_andn2_saveexec_b64 s[8:9], s[8:9]
	v_fmamk_f32 v123, v120, 0x3c088889, v125
	v_fmaak_f32 v123, v120, v123, 0x3e2aaaab
	v_fma_f32 v123, v120, v123, 0.5
	v_fma_f32 v123, v120, v123, 1.0
	v_mul_f32_e64 v123, v123, -v120
	s_or_b64 exec, exec, s[8:9]
	v_max_f32_e32 v3, v3, v3
	v_max_f32_e32 v3, 0, v3
	v_sqrt_f32_e32 v3, v3
	v_max_f32_e32 v121, v121, v121
	v_max_f32_e32 v121, 0, v121
	v_mov_b32_e32 v120, 0
	s_waitcnt lgkmcnt(1)
	v_mul_f32_e32 v3, v112, v3
	v_sqrt_f32_e32 v112, v121
	v_max_f32_e32 v121, v122, v122
	v_max_f32_e32 v121, 0, v121
	v_sqrt_f32_e32 v121, v121
	s_waitcnt lgkmcnt(0)
	v_mul_f32_e32 v116, v116, v3
	v_mul_f32_e32 v3, v113, v112
	v_mul_f32_e32 v117, v117, v3
	v_mul_f32_e32 v3, v114, v121
	v_mul_f32_e32 v118, v118, v3
	v_max_f32_e32 v3, v123, v123
	v_max_f32_e32 v3, 0, v3
	v_sqrt_f32_e32 v3, v3
	v_ashrrev_i32_e32 v114, 7, v0
	v_and_b32_e32 v121, 0x7f, v0
	v_bfe_u32 v113, v0, 6, 1
	v_mul_f32_e32 v3, v115, v3
	v_mul_f32_e32 v119, v119, v3
	ds_write_b128 v2, v[108:111] offset:25600
	ds_write_b128 v2, v[116:119] offset:58368
	v_lshlrev_b32_e32 v2, 4, v114
	v_or_b32_e32 v115, 2, v2
	v_and_b32_e32 v112, 63, v0
	v_cmp_gt_u32_e32 vcc, 64, v121
	v_sub_u32_e32 v116, 63, v115
	v_lshl_or_b32 v3, v113, 12, v112
	v_cndmask_b32_e32 v115, v116, v115, vcc
	v_lshl_add_u32 v115, v115, 6, v3
	v_lshl_add_u32 v115, v115, 2, 0
	s_waitcnt lgkmcnt(0)
	s_barrier
	ds_read2st64_b32 v[116:117], v115 offset0:100 offset1:228
	v_or_b32_e32 v115, 3, v2
	v_sub_u32_e32 v118, 63, v115
	v_cndmask_b32_e32 v115, v118, v115, vcc
	v_lshl_add_u32 v115, v115, 6, v3
	v_lshl_add_u32 v115, v115, 2, 0
	ds_read2st64_b32 v[118:119], v115 offset0:100 offset1:228
	v_or_b32_e32 v115, 4, v2
	v_sub_u32_e32 v122, 63, v115
	v_cndmask_b32_e32 v115, v122, v115, vcc
	v_lshl_add_u32 v115, v115, 6, v3
	v_lshl_add_u32 v115, v115, 2, 0
	ds_read2st64_b32 v[122:123], v115 offset0:100 offset1:228
	v_or_b32_e32 v115, 5, v2
	v_sub_u32_e32 v127, 63, v115
	v_cndmask_b32_e32 v115, v127, v115, vcc
	v_lshl_add_u32 v115, v115, 6, v3
	v_lshl_add_u32 v115, v115, 2, 0
	ds_read2st64_b32 v[128:129], v115 offset0:100 offset1:228
	v_or_b32_e32 v115, 6, v2
	v_sub_u32_e32 v127, 63, v115
	v_cndmask_b32_e32 v115, v127, v115, vcc
	v_lshl_add_u32 v115, v115, 6, v3
	v_lshl_add_u32 v115, v115, 2, 0
	ds_read2st64_b32 v[130:131], v115 offset0:100 offset1:228
	v_or_b32_e32 v115, 7, v2
	v_sub_u32_e32 v127, 63, v115
	v_cndmask_b32_e32 v115, v127, v115, vcc
	v_lshl_add_u32 v115, v115, 6, v3
	v_lshl_add_u32 v115, v115, 2, 0
	ds_read2st64_b32 v[132:133], v115 offset0:100 offset1:228
	v_or_b32_e32 v115, 8, v2
	v_sub_u32_e32 v127, 63, v115
	v_cndmask_b32_e32 v115, v127, v115, vcc
	v_lshl_add_u32 v115, v115, 6, v3
	v_lshl_add_u32 v115, v115, 2, 0
	ds_read2st64_b32 v[134:135], v115 offset0:100 offset1:228
	v_or_b32_e32 v115, 9, v2
	v_sub_u32_e32 v127, 63, v115
	v_cndmask_b32_e32 v115, v127, v115, vcc
	v_lshl_add_u32 v115, v115, 6, v3
	v_lshl_add_u32 v115, v115, 2, 0
	ds_read2st64_b32 v[136:137], v115 offset0:100 offset1:228
	v_or_b32_e32 v115, 10, v2
	v_sub_u32_e32 v127, 63, v115
	v_cndmask_b32_e32 v115, v127, v115, vcc
	v_lshl_add_u32 v115, v115, 6, v3
	v_lshl_add_u32 v115, v115, 2, 0
	ds_read2st64_b32 v[138:139], v115 offset0:100 offset1:228
	v_or_b32_e32 v115, 11, v2
	v_sub_u32_e32 v127, 63, v115
	v_cndmask_b32_e32 v115, v127, v115, vcc
	v_lshl_add_u32 v115, v115, 6, v3
	v_lshl_add_u32 v115, v115, 2, 0
	v_sub_u32_e32 v108, 63, v2
	v_or_b32_e32 v110, 1, v2
	ds_read2st64_b32 v[140:141], v115 offset0:100 offset1:228
	v_or_b32_e32 v115, 12, v2
	v_cndmask_b32_e32 v108, v108, v2, vcc
	v_sub_u32_e32 v111, 63, v110
	v_sub_u32_e32 v127, 63, v115
	v_lshl_add_u32 v108, v108, 6, v3
	v_cndmask_b32_e32 v110, v111, v110, vcc
	v_cndmask_b32_e32 v115, v127, v115, vcc
	v_lshl_add_u32 v108, v108, 2, 0
	v_lshl_add_u32 v110, v110, 6, v3
	v_lshl_add_u32 v115, v115, 6, v3
	ds_read2st64_b32 v[108:109], v108 offset0:100 offset1:228
	v_lshl_add_u32 v110, v110, 2, 0
	v_lshl_add_u32 v115, v115, 2, 0
	ds_read2st64_b32 v[110:111], v110 offset0:100 offset1:228
	ds_read2st64_b32 v[142:143], v115 offset0:100 offset1:228
	v_or_b32_e32 v115, 13, v2
	v_sub_u32_e32 v127, 63, v115
	v_cndmask_b32_e32 v115, v127, v115, vcc
	v_lshl_add_u32 v115, v115, 6, v3
	v_lshl_add_u32 v115, v115, 2, 0
	s_waitcnt lgkmcnt(2)
	v_fma_f32 v109, 0, v108, v109
	ds_read2st64_b32 v[144:145], v115 offset0:100 offset1:228
	v_or_b32_e32 v115, 14, v2
	s_waitcnt lgkmcnt(2)
	v_mul_f32_e32 v108, v108, v110
	v_fmac_f32_e32 v111, v109, v110
	v_sub_u32_e32 v127, 63, v115
	v_mul_f32_e32 v108, v108, v116
	v_fmac_f32_e32 v117, v111, v116
	v_cndmask_b32_e32 v115, v127, v115, vcc
	v_mul_f32_e32 v108, v108, v118
	v_fmac_f32_e32 v119, v117, v118
	v_lshl_add_u32 v115, v115, 6, v3
	v_mul_f32_e32 v108, v108, v122
	v_fmac_f32_e32 v123, v119, v122
	v_lshl_add_u32 v115, v115, 2, 0
	v_or_b32_e32 v2, 15, v2
	v_mul_f32_e32 v108, v108, v128
	v_fmac_f32_e32 v129, v123, v128
	ds_read2st64_b32 v[146:147], v115 offset0:100 offset1:228
	v_sub_u32_e32 v115, 63, v2
	v_mul_f32_e32 v108, v108, v130
	v_fmac_f32_e32 v131, v129, v130
	v_cndmask_b32_e32 v2, v115, v2, vcc
	v_mul_f32_e32 v108, v108, v132
	v_fmac_f32_e32 v133, v131, v132
	v_lshl_add_u32 v2, v2, 6, v3
	v_mul_f32_e32 v108, v108, v134
	v_fmac_f32_e32 v135, v133, v134
	v_lshl_add_u32 v2, v2, 2, 0
	v_mul_f32_e32 v108, v108, v136
	v_fmac_f32_e32 v137, v135, v136
	ds_read2st64_b32 v[2:3], v2 offset0:100 offset1:228
	v_mul_f32_e32 v108, v108, v138
	v_fmac_f32_e32 v139, v137, v138
	v_mul_f32_e32 v108, v108, v140
	v_fmac_f32_e32 v141, v139, v140
	s_waitcnt lgkmcnt(3)
	v_mul_f32_e32 v108, v108, v142
	v_fmac_f32_e32 v143, v141, v142
	s_waitcnt lgkmcnt(2)
	v_mul_f32_e32 v108, v108, v144
	v_fmac_f32_e32 v145, v143, v144
	s_waitcnt lgkmcnt(1)
	v_mul_f32_e32 v108, v108, v146
	v_fmac_f32_e32 v147, v145, v146
	v_lshl_add_u32 v0, v0, 2, 0
	s_waitcnt lgkmcnt(0)
	v_mul_f32_e32 v108, v108, v2
	v_fmac_f32_e32 v3, v147, v2
	v_add_u32_e32 v2, 0x16400, v0
	v_add_u32_e32 v0, 0x16c00, v0
	ds_write_b32 v2, v108
	ds_write_b32 v0, v3
	v_cmp_lt_i32_e32 vcc, 0, v114
	v_mov_b32_e32 v0, 1.0
	v_lshl_add_u32 v2, v121, 2, 0
	s_waitcnt vmcnt(0) lgkmcnt(0)
	s_barrier
	s_and_saveexec_b64 s[8:9], vcc
	s_cbranch_execnz .LBB0_431
	s_or_b64 exec, exec, s[8:9]
	v_cmp_lt_i32_e32 vcc, 1, v114
	s_and_saveexec_b64 s[8:9], vcc
	s_cbranch_execnz .LBB0_432

.LBB0_363:
	v_mov_b32_e32 v0, v204
	v_and_b32_e32 v3, 0xffff0000, v68
	v_lshlrev_b32_e32 v2, 3, v0
	v_and_b32_e32 v116, 56, v2
	v_lshlrev_b32_e32 v2, 16, v68
	s_nop 0
	v_pk_fma_f32 v[2:3], v[32:33], v[2:3], v[48:49]
	v_lshlrev_b32_e32 v108, 16, v72
	v_and_b32_e32 v109, 0xffff0000, v72
	v_pk_fma_f32 v[2:3], v[8:9], v[108:109], v[2:3]
	v_lshlrev_b32_e32 v108, 16, v100
	v_and_b32_e32 v109, 0xffff0000, v100
	v_pk_fma_f32 v[2:3], v[12:13], v[108:109], v[2:3]
	v_lshlrev_b32_e32 v108, 16, v104
	v_and_b32_e32 v109, 0xffff0000, v104
	v_pk_fma_f32 v[108:109], v[16:17], v[108:109], v[2:3]
	v_lshlrev_b32_e32 v2, 16, v70
	v_and_b32_e32 v3, 0xffff0000, v70
	v_pk_fma_f32 v[2:3], v[28:29], v[2:3], v[44:45]
	v_lshlrev_b32_e32 v110, 16, v74
	v_and_b32_e32 v111, 0xffff0000, v74
	v_pk_fma_f32 v[2:3], v[4:5], v[110:111], v[2:3]
	v_lshlrev_b32_e32 v110, 16, v102
	v_and_b32_e32 v111, 0xffff0000, v102
	v_pk_fma_f32 v[2:3], v[20:21], v[110:111], v[2:3]
	v_lshlrev_b32_e32 v110, 16, v106
	v_and_b32_e32 v111, 0xffff0000, v106
	v_pk_fma_f32 v[112:113], v[36:37], v[110:111], v[2:3]
	v_lshlrev_b32_e32 v2, 16, v69
	v_and_b32_e32 v3, 0xffff0000, v69
	v_pk_fma_f32 v[2:3], v[34:35], v[2:3], v[50:51]
	v_lshlrev_b32_e32 v110, 16, v73
	v_and_b32_e32 v111, 0xffff0000, v73
	v_pk_fma_f32 v[2:3], v[10:11], v[110:111], v[2:3]
	v_lshlrev_b32_e32 v110, 16, v101
	v_and_b32_e32 v111, 0xffff0000, v101
	v_pk_fma_f32 v[2:3], v[14:15], v[110:111], v[2:3]
	v_lshlrev_b32_e32 v110, 16, v105
	v_and_b32_e32 v111, 0xffff0000, v105
	v_pk_fma_f32 v[110:111], v[18:19], v[110:111], v[2:3]
	v_lshlrev_b32_e32 v2, 16, v71
	v_and_b32_e32 v3, 0xffff0000, v71
	v_pk_fma_f32 v[2:3], v[30:31], v[2:3], v[46:47]
	v_lshlrev_b32_e32 v114, 16, v75
	v_and_b32_e32 v115, 0xffff0000, v75
	v_pk_fma_f32 v[2:3], v[6:7], v[114:115], v[2:3]
	v_lshlrev_b32_e32 v114, 16, v103
	v_and_b32_e32 v115, 0xffff0000, v103
	v_pk_fma_f32 v[2:3], v[22:23], v[114:115], v[2:3]
	v_lshlrev_b32_e32 v114, 16, v107
	v_and_b32_e32 v115, 0xffff0000, v107
	v_pk_fma_f32 v[114:115], v[38:39], v[114:115], v[2:3]
	v_ashrrev_i32_e32 v3, 3, v0
	v_lshl_add_u32 v117, v3, 8, 0
	v_lshl_add_u32 v118, v116, 2, v117
	ds_write_b128 v118, v[108:111]
	ds_write_b128 v118, v[112:115] offset:16
	v_cvt_pk_bf16_f32 v108, v108, v109
	v_cvt_pk_bf16_f32 v109, v110, v111
	v_cvt_pk_bf16_f32 v110, v112, v113
	v_mul_lo_u32 v3, v3, s67
	v_lshlrev_b32_e32 v112, 1, v116
	v_and_b32_e32 v127, 15, v0
	v_cvt_pk_bf16_f32 v111, v114, v115
	v_add3_u32 v3, v117, v3, v112
	v_and_b32_e32 v2, 48, v0
	ds_write_b128 v3, v[108:111] offset:16384
	v_mul_u32_u24_e32 v3, 0x90, v127
	v_add3_u32 v3, 0, v2, v3
	s_waitcnt lgkmcnt(0)
	s_barrier
	ds_read_b128 v[108:111], v3 offset:16384
	ds_read_b128 v[112:115], v3 offset:16448
	ds_read_b128 v[120:123], v3 offset:18688
	ds_read_b128 v[128:131], v3 offset:18752
	ds_read_b128 v[136:139], v3 offset:20992
	ds_read_b128 v[140:143], v3 offset:21056
	s_waitcnt lgkmcnt(5)
	v_mfma_f32_16x16x32_bf16 v[116:119], v[60:63], v[108:111], 0
	ds_read_b128 v[148:151], v3 offset:23296
	ds_read_b128 v[154:157], v3 offset:23360
	v_mov_b32_e32 v3, s2
	v_cmp_gt_u32_e32 vcc, s45, v0
	s_nop 0
	v_mfma_f32_16x16x32_bf16 v[108:111], v[76:79], v[108:111], 0
	v_lshlrev_b32_e32 v127, 8, v127
	s_waitcnt lgkmcnt(3)
	v_mfma_f32_16x16x32_bf16 v[144:147], v[60:63], v[136:139], 0
	v_mfma_f32_16x16x32_bf16 v[136:139], v[76:79], v[136:139], 0
	v_mfma_f32_16x16x32_bf16 v[162:165], v[64:67], v[112:115], v[116:119]
	s_nop 0
	v_mfma_f32_16x16x32_bf16 v[166:169], v[80:83], v[112:115], v[108:111]
	s_waitcnt lgkmcnt(2)
	v_mfma_f32_16x16x32_bf16 v[112:115], v[80:83], v[140:143], v[136:139]
	s_nop 2
	v_mov_b32_e32 v136, s73
	v_cndmask_b32_e32 v3, v3, v136, vcc
	v_lshlrev_b32_e32 v136, 7, v0
	v_and_b32_e32 v136, 0x4000, v136
	v_add3_u32 v3, v3, v136, v127
	s_nop 0
	v_add_f32_e32 v136, v84, v162
	v_mul_f32_e32 v136, 0xbfb8aa3b, v136
	v_add_f32_e32 v137, v85, v163
	v_exp_f32_e32 v136, v136
	v_mul_f32_e32 v137, 0xbfb8aa3b, v137
	v_exp_f32_e32 v137, v137
	v_lshlrev_b32_e32 v127, 1, v0
	v_and_b32_e32 v127, 0x80, v127
	v_add_f32_e32 v136, 1.0, v136
	v_rcp_f32_e32 v136, v136
	v_add3_u32 v2, v3, v127, v2
	v_add_f32_e32 v3, 1.0, v137
	v_add_f32_e32 v137, v86, v164
	v_mul_f32_e32 v137, 0xbfb8aa3b, v137
	v_rcp_f32_e32 v3, v3
	v_exp_f32_e32 v137, v137
	v_add_f32_e32 v138, v87, v165
	v_mul_f32_e32 v138, 0xbfb8aa3b, v138
	v_mul_f32_e32 v127, 0xc1000000, v136
	v_exp_f32_e32 v138, v138
	s_nop 0
	v_mul_f32_e32 v127, v92, v127
	v_cndmask_b32_e32 v136, v136, v127, vcc
	v_mul_f32_e32 v127, 0xc1000000, v3
	v_add_f32_e32 v137, 1.0, v137
	v_mfma_f32_16x16x32_bf16 v[132:135], v[60:63], v[120:123], 0
	v_mul_f32_e32 v127, v93, v127
	v_rcp_f32_e32 v139, v137
	v_cndmask_b32_e32 v137, v3, v127, vcc
	v_add_f32_e32 v3, 1.0, v138
	v_rcp_f32_e32 v3, v3
	v_mfma_f32_16x16x32_bf16 v[132:135], v[64:67], v[128:131], v[132:135]
	v_mul_f32_e32 v127, 0xc1000000, v139
	v_mul_f32_e32 v127, v94, v127
	v_cndmask_b32_e32 v138, v139, v127, vcc
	v_mul_f32_e32 v127, 0xc1000000, v3
	v_mul_f32_e32 v127, v95, v127
	v_cndmask_b32_e32 v139, v3, v127, vcc
	s_nop 1
	v_add_f32_e32 v3, v84, v132
	v_mul_f32_e32 v3, 0xbfb8aa3b, v3
	v_exp_f32_e32 v3, v3
	v_add_f32_e32 v127, v85, v133
	v_mul_f32_e32 v127, 0xbfb8aa3b, v127
	v_exp_f32_e32 v127, v127
	v_add_f32_e32 v3, 1.0, v3
	v_rcp_f32_e32 v3, v3
	v_add_f32_e32 v133, v86, v134
	v_add_f32_e32 v127, 1.0, v127
	v_mul_f32_e32 v133, 0xbfb8aa3b, v133
	v_rcp_f32_e32 v127, v127
	v_exp_f32_e32 v133, v133
	v_add_f32_e32 v134, v87, v135
	v_mul_f32_e32 v134, 0xbfb8aa3b, v134
	v_mul_f32_e32 v132, 0xc1000000, v3
	v_exp_f32_e32 v134, v134
	v_mul_f32_e32 v132, v92, v132
	v_cndmask_b32_e32 v132, v3, v132, vcc
	v_mul_f32_e32 v3, 0xc1000000, v127
	v_add_f32_e32 v133, 1.0, v133
	v_mfma_f32_16x16x32_bf16 v[120:123], v[76:79], v[120:123], 0
	v_mul_f32_e32 v3, v93, v3
	v_rcp_f32_e32 v135, v133
	v_cndmask_b32_e32 v133, v127, v3, vcc
	v_add_f32_e32 v3, 1.0, v134
	v_rcp_f32_e32 v3, v3
	v_mfma_f32_16x16x32_bf16 v[116:119], v[80:83], v[128:131], v[120:123]
	v_mul_f32_e32 v127, 0xc1000000, v135
	v_mul_f32_e32 v127, v94, v127
	v_cndmask_b32_e32 v134, v135, v127, vcc
	v_mfma_f32_16x16x32_bf16 v[120:123], v[64:67], v[140:143], v[144:147]
	v_mul_f32_e32 v127, 0xc1000000, v3
	v_mul_f32_e32 v127, v95, v127
	v_cndmask_b32_e32 v135, v3, v127, vcc
	s_waitcnt lgkmcnt(1)
	v_mfma_f32_16x16x32_bf16 v[158:161], v[60:63], v[148:151], 0
	v_add_f32_e32 v118, v90, v118
	s_nop 1
	v_add_f32_e32 v3, v84, v120
	v_mul_f32_e32 v3, 0xbfb8aa3b, v3
	v_exp_f32_e32 v3, v3
	v_add_f32_e32 v120, v85, v121
	v_mul_f32_e32 v120, 0xbfb8aa3b, v120
	v_exp_f32_e32 v120, v120
	v_add_f32_e32 v3, 1.0, v3
	v_rcp_f32_e32 v3, v3
	v_add_f32_e32 v122, v86, v122
	v_add_f32_e32 v120, 1.0, v120
	v_mul_f32_e32 v122, 0xbfb8aa3b, v122
	v_rcp_f32_e32 v121, v120
	v_exp_f32_e32 v122, v122
	v_add_f32_e32 v123, v87, v123
	v_mul_f32_e32 v123, 0xbfb8aa3b, v123
	v_mul_f32_e32 v120, 0xc1000000, v3
	v_exp_f32_e32 v123, v123
	v_mul_f32_e32 v120, v92, v120
	v_cndmask_b32_e32 v120, v3, v120, vcc
	v_mul_f32_e32 v3, 0xc1000000, v121
	v_add_f32_e32 v122, 1.0, v122
	v_mul_f32_e32 v3, v93, v3
	v_rcp_f32_e32 v122, v122
	v_cndmask_b32_e32 v121, v121, v3, vcc
	v_add_f32_e32 v3, 1.0, v123
	v_rcp_f32_e32 v3, v3
	s_waitcnt lgkmcnt(0)
	v_mfma_f32_16x16x32_bf16 v[128:131], v[64:67], v[154:157], v[158:161]
	ds_write_b128 v2, v[136:139]
	ds_write_b128 v2, v[132:135] offset:4096
	v_mul_f32_e32 v123, 0xc1000000, v122
	v_mul_f32_e32 v123, v94, v123
	v_cndmask_b32_e32 v122, v122, v123, vcc
	v_mul_f32_e32 v123, 0xc1000000, v3
	v_mul_f32_e32 v123, v95, v123
	v_cndmask_b32_e32 v123, v3, v123, vcc
	s_nop 1
	v_add_f32_e32 v3, v84, v128
	v_mul_f32_e32 v3, 0xbfb8aa3b, v3
	v_exp_f32_e32 v3, v3
	v_add_f32_e32 v127, v85, v129
	v_mul_f32_e32 v127, 0xbfb8aa3b, v127
	v_exp_f32_e32 v127, v127
	v_add_f32_e32 v3, 1.0, v3
	v_rcp_f32_e32 v3, v3
	ds_write_b128 v2, v[120:123] offset:8192
	v_add_f32_e32 v122, v86, v130
	v_add_f32_e32 v120, 1.0, v127
	v_mul_f32_e32 v122, 0xbfb8aa3b, v122
	v_rcp_f32_e32 v121, v120
	v_exp_f32_e32 v122, v122
	v_add_f32_e32 v123, v87, v131
	v_mul_f32_e32 v123, 0xbfb8aa3b, v123
	v_mul_f32_e32 v120, 0xc1000000, v3
	v_exp_f32_e32 v123, v123
	v_mul_f32_e32 v120, v92, v120
	v_cndmask_b32_e32 v120, v3, v120, vcc
	v_mul_f32_e32 v3, 0xc1000000, v121
	v_add_f32_e32 v122, 1.0, v122
	v_mul_f32_e32 v3, v93, v3
	v_rcp_f32_e32 v122, v122
	v_cndmask_b32_e32 v121, v121, v3, vcc
	v_add_f32_e32 v3, 1.0, v123
	v_rcp_f32_e32 v3, v3
	v_mul_f32_e32 v123, 0xc1000000, v122
	v_mul_f32_e32 v123, v94, v123
	v_cndmask_b32_e32 v122, v122, v123, vcc
	v_mul_f32_e32 v123, 0xc1000000, v3
	v_mul_f32_e32 v123, v95, v123
	v_cndmask_b32_e32 v123, v3, v123, vcc
	v_add_f32_e32 v3, v88, v166
	v_mul_f32_e32 v3, 0xbfb8aa3b, v3
	v_exp_f32_e32 v3, v3
	v_add_f32_e32 v127, v89, v167
	v_mul_f32_e32 v127, 0xbfb8aa3b, v127
	v_exp_f32_e32 v127, v127
	v_add_f32_e32 v3, 1.0, v3
	v_rcp_f32_e32 v3, v3
	ds_write_b128 v2, v[120:123] offset:12288
	v_add_f32_e32 v122, v90, v168
	v_add_f32_e32 v120, 1.0, v127
	v_mul_f32_e32 v122, 0xbfb8aa3b, v122
	v_rcp_f32_e32 v121, v120
	v_exp_f32_e32 v122, v122
	v_add_f32_e32 v123, v91, v169
	v_mul_f32_e32 v123, 0xbfb8aa3b, v123
	v_mul_f32_e32 v120, 0xc1000000, v3
	v_exp_f32_e32 v123, v123
	s_nop 0
	v_mul_f32_e32 v120, v96, v120
	v_cndmask_b32_e32 v120, v3, v120, vcc
	v_mul_f32_e32 v3, 0xc1000000, v121
	v_add_f32_e32 v122, 1.0, v122
	v_mul_f32_e32 v3, v97, v3
	v_rcp_f32_e32 v122, v122
	v_cndmask_b32_e32 v121, v121, v3, vcc
	v_add_f32_e32 v3, 1.0, v123
	v_rcp_f32_e32 v3, v3
	v_mul_f32_e32 v123, 0xc1000000, v122
	v_mul_f32_e32 v123, v98, v123
	v_cndmask_b32_e32 v122, v122, v123, vcc
	v_mul_f32_e32 v123, 0xc1000000, v3
	v_mul_f32_e32 v123, v99, v123
	v_cndmask_b32_e32 v123, v3, v123, vcc
	v_add_f32_e32 v3, v88, v116
	ds_write_b128 v2, v[120:123] offset:64
	v_mul_f32_e32 v3, 0xbfb8aa3b, v3
	v_exp_f32_e32 v3, v3
	v_add_f32_e32 v116, v89, v117
	v_mul_f32_e32 v116, 0xbfb8aa3b, v116
	v_exp_f32_e32 v116, v116
	v_add_f32_e32 v3, 1.0, v3
	v_rcp_f32_e32 v3, v3
	v_mul_f32_e32 v118, 0xbfb8aa3b, v118
	v_add_f32_e32 v116, 1.0, v116
	v_rcp_f32_e32 v117, v116
	v_exp_f32_e32 v118, v118
	v_add_f32_e32 v119, v91, v119
	v_mul_f32_e32 v119, 0xbfb8aa3b, v119
	v_mul_f32_e32 v116, 0xc1000000, v3
	v_exp_f32_e32 v119, v119
	v_mul_f32_e32 v116, v96, v116
	v_cndmask_b32_e32 v116, v3, v116, vcc
	v_mul_f32_e32 v3, 0xc1000000, v117
	v_add_f32_e32 v118, 1.0, v118
	v_mul_f32_e32 v3, v97, v3
	v_rcp_f32_e32 v118, v118
	v_cndmask_b32_e32 v117, v117, v3, vcc
	v_add_f32_e32 v3, 1.0, v119
	v_rcp_f32_e32 v3, v3
	v_mul_f32_e32 v119, 0xc1000000, v118
	v_mul_f32_e32 v119, v98, v119
	v_cndmask_b32_e32 v118, v118, v119, vcc
	v_mul_f32_e32 v119, 0xc1000000, v3
	v_mul_f32_e32 v119, v99, v119
	v_cndmask_b32_e32 v119, v3, v119, vcc
	v_add_f32_e32 v3, v88, v112
	ds_write_b128 v2, v[116:119] offset:4160
	v_mul_f32_e32 v3, 0xbfb8aa3b, v3
	v_exp_f32_e32 v3, v3
	v_add_f32_e32 v112, v89, v113
	v_mul_f32_e32 v112, 0xbfb8aa3b, v112
	v_exp_f32_e32 v112, v112
	v_add_f32_e32 v3, 1.0, v3
	v_rcp_f32_e32 v3, v3
	v_add_f32_e32 v114, v90, v114
	v_add_f32_e32 v112, 1.0, v112
	v_mul_f32_e32 v114, 0xbfb8aa3b, v114
	v_rcp_f32_e32 v113, v112
	v_exp_f32_e32 v114, v114
	v_add_f32_e32 v115, v91, v115
	v_mul_f32_e32 v115, 0xbfb8aa3b, v115
	v_mul_f32_e32 v112, 0xc1000000, v3
	v_exp_f32_e32 v115, v115
	v_mul_f32_e32 v112, v96, v112
	v_cndmask_b32_e32 v112, v3, v112, vcc
	v_mul_f32_e32 v3, 0xc1000000, v113
	v_add_f32_e32 v114, 1.0, v114
	v_mfma_f32_16x16x32_bf16 v[148:151], v[76:79], v[148:151], 0
	v_mul_f32_e32 v3, v97, v3
	v_rcp_f32_e32 v114, v114
	v_cndmask_b32_e32 v113, v113, v3, vcc
	v_add_f32_e32 v3, 1.0, v115
	v_rcp_f32_e32 v3, v3
	v_mfma_f32_16x16x32_bf16 v[108:111], v[80:83], v[154:157], v[148:151]
	v_mul_f32_e32 v115, 0xc1000000, v114
	v_mul_f32_e32 v115, v98, v115
	v_cndmask_b32_e32 v114, v114, v115, vcc
	v_mul_f32_e32 v115, 0xc1000000, v3
	v_mul_f32_e32 v115, v99, v115
	v_cndmask_b32_e32 v115, v3, v115, vcc
	s_nop 1
	ds_write_b128 v2, v[112:115] offset:8256
	v_add_f32_e32 v3, v88, v108
	v_mul_f32_e32 v3, 0xbfb8aa3b, v3
	v_exp_f32_e32 v3, v3
	v_add_f32_e32 v108, v89, v109
	v_mul_f32_e32 v108, 0xbfb8aa3b, v108
	v_exp_f32_e32 v108, v108
	v_add_f32_e32 v3, 1.0, v3
	v_rcp_f32_e32 v3, v3
	v_add_f32_e32 v110, v90, v110
	v_add_f32_e32 v108, 1.0, v108
	v_mul_f32_e32 v110, 0xbfb8aa3b, v110
	v_rcp_f32_e32 v109, v108
	v_exp_f32_e32 v110, v110
	v_add_f32_e32 v111, v91, v111
	v_mul_f32_e32 v111, 0xbfb8aa3b, v111
	v_mul_f32_e32 v108, 0xc1000000, v3
	v_exp_f32_e32 v111, v111
	v_mul_f32_e32 v108, v96, v108
	v_cndmask_b32_e32 v108, v3, v108, vcc
	v_mul_f32_e32 v3, 0xc1000000, v109
	v_add_f32_e32 v110, 1.0, v110
	v_mul_f32_e32 v3, v97, v3
	v_rcp_f32_e32 v110, v110
	v_cndmask_b32_e32 v109, v109, v3, vcc
	v_add_f32_e32 v3, 1.0, v111
	v_rcp_f32_e32 v3, v3
	v_mul_f32_e32 v111, 0xc1000000, v110
	v_mul_f32_e32 v111, v98, v111
	v_cndmask_b32_e32 v110, v110, v111, vcc
	v_mul_f32_e32 v111, 0xc1000000, v3
	v_mul_f32_e32 v111, v99, v111
	v_cndmask_b32_e32 v111, v3, v111, vcc
	ds_write_b128 v2, v[108:111] offset:12352
	v_lshlrev_b32_e32 v3, 2, v0
	v_lshlrev_b32_e32 v108, 4, v0


	v_and_b32_e32 v2, 60, v3
	v_and_b32_e32 v109, 0xffffc000, v108
	v_lshlrev_b32_e32 v2, 2, v2
	v_add_u32_e32 v109, 0, v109
	v_and_b32_e32 v108, 0x3f00, v108
	v_add3_u32 v128, v109, v108, v2
	s_waitcnt lgkmcnt(0)
	s_barrier
	ds_read_b128 v[120:123], v128 offset:25600
	ds_read_b128 v[112:115], v128 offset:58368
	v_add_u32_e32 v127, 0, v2
	v_add_u32_e32 v129, v127, v108
	ds_read_b128 v[116:119], v129
	s_waitcnt lgkmcnt(2)
	v_mul_f32_e32 v108, 0x3fb8aa3b, v120
	v_exp_f32_e32 v108, v108
	v_add_f32_e32 v109, v120, v120
	v_cmp_nlt_f32_e32 vcc, s75, v109
	s_and_saveexec_b64 s[6:7], vcc
	s_xor_b64 s[6:7], exec, s[6:7]
	v_fma_f32 v120, -v108, v108, 1.0
	s_andn2_saveexec_b64 s[6:7], s[6:7]
	v_fmamk_f32 v110, v109, 0x3c088889, v125
	v_fmaak_f32 v110, v109, v110, 0x3e2aaaab
	v_fma_f32 v110, v109, v110, 0.5
	v_fma_f32 v110, v109, v110, 1.0
	v_mul_f32_e64 v120, v110, -v109
	s_or_b64 exec, exec, s[6:7]
	v_mul_f32_e32 v109, 0x3fb8aa3b, v121
	v_exp_f32_e32 v109, v109
	v_add_f32_e32 v110, v121, v121
	v_cmp_nlt_f32_e32 vcc, s75, v110
	s_and_saveexec_b64 s[6:7], vcc
	s_xor_b64 s[6:7], exec, s[6:7]
	v_fma_f32 v121, -v109, v109, 1.0
	s_andn2_saveexec_b64 s[6:7], s[6:7]
	v_fmamk_f32 v111, v110, 0x3c088889, v125
	v_fmaak_f32 v111, v110, v111, 0x3e2aaaab
	v_fma_f32 v111, v110, v111, 0.5
	v_fma_f32 v111, v110, v111, 1.0
	v_mul_f32_e64 v121, v111, -v110
	s_or_b64 exec, exec, s[6:7]
	v_mul_f32_e32 v110, 0x3fb8aa3b, v122
	v_exp_f32_e32 v110, v110
	v_add_f32_e32 v111, v122, v122
	v_cmp_nlt_f32_e32 vcc, s75, v111
	s_and_saveexec_b64 s[6:7], vcc
	s_xor_b64 s[6:7], exec, s[6:7]
	v_fma_f32 v122, -v110, v110, 1.0
	s_andn2_saveexec_b64 s[6:7], s[6:7]
	v_fmamk_f32 v122, v111, 0x3c088889, v125
	v_fmaak_f32 v122, v111, v122, 0x3e2aaaab
	v_fma_f32 v122, v111, v122, 0.5
	v_fma_f32 v122, v111, v122, 1.0
	v_mul_f32_e64 v122, v122, -v111
	s_or_b64 exec, exec, s[6:7]
	v_mul_f32_e32 v111, 0x3fb8aa3b, v123
	v_exp_f32_e32 v111, v111
	v_add_f32_e32 v130, v123, v123
	v_cmp_nlt_f32_e32 vcc, s75, v130
	s_and_saveexec_b64 s[6:7], vcc
	s_xor_b64 s[6:7], exec, s[6:7]
	v_fma_f32 v123, -v111, v111, 1.0
	s_andn2_saveexec_b64 s[6:7], s[6:7]
	v_fmamk_f32 v123, v130, 0x3c088889, v125
	v_fmaak_f32 v123, v130, v123, 0x3e2aaaab
	v_fma_f32 v123, v130, v123, 0.5
	v_fma_f32 v123, v130, v123, 1.0
	v_mul_f32_e64 v123, v123, -v130
	s_or_b64 exec, exec, s[6:7]
	v_max_f32_e32 v120, v120, v120
	v_max_f32_e32 v120, 0, v120
	v_sqrt_f32_e32 v120, v120
	v_max_f32_e32 v121, v121, v121
	v_max_f32_e32 v121, 0, v121
	v_sqrt_f32_e32 v121, v121
	s_waitcnt lgkmcnt(1)
	v_mul_f32_e32 v112, v112, v120
	s_waitcnt lgkmcnt(0)
	v_mul_f32_e32 v112, v116, v112
	v_max_f32_e32 v116, v122, v122
	v_max_f32_e32 v120, v123, v123
	v_max_f32_e32 v116, 0, v116
	v_max_f32_e32 v120, 0, v120
	v_sqrt_f32_e32 v116, v116
	v_sqrt_f32_e32 v120, v120
	v_mul_f32_e32 v113, v113, v121
	v_mul_f32_e32 v113, v117, v113
	v_mul_f32_e32 v114, v114, v116
	v_mul_f32_e32 v115, v115, v120
	v_mul_f32_e32 v114, v118, v114
	v_mul_f32_e32 v115, v119, v115
	ds_write_b128 v128, v[108:111] offset:25600
	ds_write_b128 v128, v[112:115] offset:58368
	v_add_u32_e32 v108, 0x800, v3
	v_and_b32_e32 v109, 0x3ffff000, v108
	v_and_b32_e32 v108, 0xfc0, v108
	v_lshl_add_u32 v109, v109, 2, 0
	v_lshlrev_b32_e32 v108, 2, v108
	v_add3_u32 v130, v109, v108, v2
	ds_read_b128 v[120:123], v130 offset:25600
	ds_read_b128 v[112:115], v130 offset:58368
	v_add_u32_e32 v108, v127, v108
	ds_read_b128 v[116:119], v108
	s_waitcnt lgkmcnt(2)
	v_mul_f32_e32 v108, 0x3fb8aa3b, v120
	v_exp_f32_e32 v108, v108
	v_add_f32_e32 v109, v120, v120
	v_cmp_nlt_f32_e32 vcc, s75, v109
	s_and_saveexec_b64 s[6:7], vcc
	s_xor_b64 s[6:7], exec, s[6:7]
	v_fma_f32 v120, -v108, v108, 1.0
	s_andn2_saveexec_b64 s[6:7], s[6:7]
	v_fmamk_f32 v110, v109, 0x3c088889, v125
	v_fmaak_f32 v110, v109, v110, 0x3e2aaaab
	v_fma_f32 v110, v109, v110, 0.5
	v_fma_f32 v110, v109, v110, 1.0
	v_mul_f32_e64 v120, v110, -v109
	s_or_b64 exec, exec, s[6:7]
	v_mul_f32_e32 v109, 0x3fb8aa3b, v121
	v_exp_f32_e32 v109, v109
	v_add_f32_e32 v110, v121, v121
	v_cmp_nlt_f32_e32 vcc, s75, v110
	s_and_saveexec_b64 s[6:7], vcc
	s_xor_b64 s[6:7], exec, s[6:7]
	v_fma_f32 v121, -v109, v109, 1.0
	s_andn2_saveexec_b64 s[6:7], s[6:7]
	v_fmamk_f32 v111, v110, 0x3c088889, v125
	v_fmaak_f32 v111, v110, v111, 0x3e2aaaab
	v_fma_f32 v111, v110, v111, 0.5
	v_fma_f32 v111, v110, v111, 1.0
	v_mul_f32_e64 v121, v111, -v110
	s_or_b64 exec, exec, s[6:7]
	v_mul_f32_e32 v110, 0x3fb8aa3b, v122
	v_exp_f32_e32 v110, v110
	v_add_f32_e32 v111, v122, v122
	v_cmp_nlt_f32_e32 vcc, s75, v111
	s_and_saveexec_b64 s[6:7], vcc
	s_xor_b64 s[6:7], exec, s[6:7]
	v_fma_f32 v122, -v110, v110, 1.0
	s_andn2_saveexec_b64 s[6:7], s[6:7]
	v_fmamk_f32 v122, v111, 0x3c088889, v125
	v_fmaak_f32 v122, v111, v122, 0x3e2aaaab
	v_fma_f32 v122, v111, v122, 0.5
	v_fma_f32 v122, v111, v122, 1.0
	v_mul_f32_e64 v122, v122, -v111
	s_or_b64 exec, exec, s[6:7]
	v_mul_f32_e32 v111, 0x3fb8aa3b, v123
	v_exp_f32_e32 v111, v111
	v_add_f32_e32 v131, v123, v123
	v_cmp_nlt_f32_e32 vcc, s75, v131
	s_and_saveexec_b64 s[6:7], vcc
	s_xor_b64 s[6:7], exec, s[6:7]
	v_fma_f32 v123, -v111, v111, 1.0
	s_andn2_saveexec_b64 s[6:7], s[6:7]
	v_fmamk_f32 v123, v131, 0x3c088889, v125
	v_fmaak_f32 v123, v131, v123, 0x3e2aaaab
	v_fma_f32 v123, v131, v123, 0.5
	v_fma_f32 v123, v131, v123, 1.0
	v_mul_f32_e64 v123, v123, -v131
	s_or_b64 exec, exec, s[6:7]
	v_max_f32_e32 v120, v120, v120
	v_max_f32_e32 v120, 0, v120
	v_sqrt_f32_e32 v120, v120
	v_max_f32_e32 v121, v121, v121
	v_max_f32_e32 v121, 0, v121
	v_sqrt_f32_e32 v121, v121
	s_waitcnt lgkmcnt(1)
	v_mul_f32_e32 v112, v112, v120
	s_waitcnt lgkmcnt(0)
	v_mul_f32_e32 v112, v116, v112
	v_max_f32_e32 v116, v122, v122
	v_max_f32_e32 v120, v123, v123
	v_max_f32_e32 v116, 0, v116
	v_max_f32_e32 v120, 0, v120
	v_sqrt_f32_e32 v116, v116
	v_sqrt_f32_e32 v120, v120
	v_mul_f32_e32 v113, v113, v121
	v_mul_f32_e32 v113, v117, v113
	v_mul_f32_e32 v114, v114, v116
	v_mul_f32_e32 v115, v115, v120
	v_mul_f32_e32 v114, v118, v114
	v_mul_f32_e32 v115, v119, v115
	ds_write_b128 v130, v[108:111] offset:25600
	ds_write_b128 v130, v[112:115] offset:58368
	ds_read_b128 v[120:123], v128 offset:41984
	v_add_u32_e32 v130, 0xe400, v128
	ds_read_b128 v[112:115], v130 offset:16384
	ds_read_b128 v[116:119], v129
	s_waitcnt lgkmcnt(2)
	v_mul_f32_e32 v108, 0x3fb8aa3b, v120
	v_exp_f32_e32 v108, v108
	v_add_f32_e32 v109, v120, v120
	v_cmp_nlt_f32_e32 vcc, s75, v109
	s_and_saveexec_b64 s[6:7], vcc
	s_xor_b64 s[6:7], exec, s[6:7]
	v_fma_f32 v120, -v108, v108, 1.0
	s_andn2_saveexec_b64 s[6:7], s[6:7]
	v_fmamk_f32 v110, v109, 0x3c088889, v125
	v_fmaak_f32 v110, v109, v110, 0x3e2aaaab
	v_fma_f32 v110, v109, v110, 0.5
	v_fma_f32 v110, v109, v110, 1.0
	v_mul_f32_e64 v120, v110, -v109
	s_or_b64 exec, exec, s[6:7]
	v_mul_f32_e32 v109, 0x3fb8aa3b, v121
	v_exp_f32_e32 v109, v109
	v_add_f32_e32 v110, v121, v121
	v_cmp_nlt_f32_e32 vcc, s75, v110
	s_and_saveexec_b64 s[6:7], vcc
	s_xor_b64 s[6:7], exec, s[6:7]
	v_fma_f32 v121, -v109, v109, 1.0
	s_andn2_saveexec_b64 s[6:7], s[6:7]
	v_fmamk_f32 v111, v110, 0x3c088889, v125
	v_fmaak_f32 v111, v110, v111, 0x3e2aaaab
	v_fma_f32 v111, v110, v111, 0.5
	v_fma_f32 v111, v110, v111, 1.0
	v_mul_f32_e64 v121, v111, -v110
	s_or_b64 exec, exec, s[6:7]
	v_mul_f32_e32 v110, 0x3fb8aa3b, v122
	v_exp_f32_e32 v110, v110
	v_add_f32_e32 v111, v122, v122
	v_cmp_nlt_f32_e32 vcc, s75, v111
	s_and_saveexec_b64 s[6:7], vcc
	s_xor_b64 s[6:7], exec, s[6:7]
	v_fma_f32 v122, -v110, v110, 1.0
	s_andn2_saveexec_b64 s[6:7], s[6:7]
	v_fmamk_f32 v122, v111, 0x3c088889, v125
	v_fmaak_f32 v122, v111, v122, 0x3e2aaaab
	v_fma_f32 v122, v111, v122, 0.5
	v_fma_f32 v122, v111, v122, 1.0
	v_mul_f32_e64 v122, v122, -v111
	s_or_b64 exec, exec, s[6:7]
	v_mul_f32_e32 v111, 0x3fb8aa3b, v123
	v_exp_f32_e32 v111, v111
	v_add_f32_e32 v129, v123, v123
	v_cmp_nlt_f32_e32 vcc, s75, v129
	s_and_saveexec_b64 s[6:7], vcc
	s_xor_b64 s[6:7], exec, s[6:7]
	v_fma_f32 v123, -v111, v111, 1.0
	s_andn2_saveexec_b64 s[6:7], s[6:7]
	v_fmamk_f32 v123, v129, 0x3c088889, v125
	v_fmaak_f32 v123, v129, v123, 0x3e2aaaab
	v_fma_f32 v123, v129, v123, 0.5
	v_fma_f32 v123, v129, v123, 1.0
	v_mul_f32_e64 v123, v123, -v129
	s_or_b64 exec, exec, s[6:7]
	v_max_f32_e32 v120, v120, v120
	v_max_f32_e32 v120, 0, v120
	v_sqrt_f32_e32 v120, v120
	v_max_f32_e32 v121, v121, v121
	v_max_f32_e32 v121, 0, v121
	v_sqrt_f32_e32 v121, v121
	s_waitcnt lgkmcnt(1)
	v_mul_f32_e32 v112, v112, v120
	s_waitcnt lgkmcnt(0)
	v_mul_f32_e32 v112, v116, v112
	v_max_f32_e32 v116, v122, v122
	v_max_f32_e32 v120, v123, v123
	v_max_f32_e32 v116, 0, v116
	v_max_f32_e32 v120, 0, v120
	v_sqrt_f32_e32 v116, v116
	v_sqrt_f32_e32 v120, v120
	v_mul_f32_e32 v113, v113, v121
	v_add_u32_e32 v3, 0x1800, v3
	v_mul_f32_e32 v114, v114, v116
	v_mul_f32_e32 v115, v115, v120
	v_mul_f32_e32 v113, v117, v113
	v_mul_f32_e32 v114, v118, v114
	v_mul_f32_e32 v115, v119, v115
	ds_write_b128 v128, v[108:111] offset:41984
	ds_write_b128 v130, v[112:115] offset:16384
	v_and_b32_e32 v108, 0x3ffff000, v3
	v_and_b32_e32 v3, 0xfc0, v3
	v_lshl_add_u32 v108, v108, 2, 0
	v_lshlrev_b32_e32 v3, 2, v3
	v_add3_u32 v2, v108, v3, v2
	ds_read_b128 v[120:123], v2 offset:25600
	ds_read_b128 v[112:115], v2 offset:58368
	v_add_u32_e32 v3, v127, v3
	ds_read_b128 v[116:119], v3
	s_waitcnt lgkmcnt(2)
	v_mul_f32_e32 v3, 0x3fb8aa3b, v120
	v_exp_f32_e32 v108, v3
	v_add_f32_e32 v109, v120, v120
	v_cmp_nlt_f32_e32 vcc, s75, v109
	s_and_saveexec_b64 s[6:7], vcc
	s_xor_b64 s[6:7], exec, s[6:7]
	v_fma_f32 v3, -v108, v108, 1.0
	s_andn2_saveexec_b64 s[6:7], s[6:7]
	v_fmamk_f32 v3, v109, 0x3c088889, v125
	v_fmaak_f32 v3, v109, v3, 0x3e2aaaab
	v_fma_f32 v3, v109, v3, 0.5
	v_fma_f32 v3, v109, v3, 1.0
	v_mul_f32_e64 v3, v3, -v109
	s_or_b64 exec, exec, s[6:7]
	v_mul_f32_e32 v109, 0x3fb8aa3b, v121
	v_exp_f32_e32 v109, v109
	v_add_f32_e32 v110, v121, v121
	v_cmp_nlt_f32_e32 vcc, s75, v110
	s_and_saveexec_b64 s[6:7], vcc
	s_xor_b64 s[6:7], exec, s[6:7]
	v_fma_f32 v121, -v109, v109, 1.0
	s_andn2_saveexec_b64 s[6:7], s[6:7]
	v_fmamk_f32 v111, v110, 0x3c088889, v125
	v_fmaak_f32 v111, v110, v111, 0x3e2aaaab
	v_fma_f32 v111, v110, v111, 0.5
	v_fma_f32 v111, v110, v111, 1.0
	v_mul_f32_e64 v121, v111, -v110
	s_or_b64 exec, exec, s[6:7]
	v_mul_f32_e32 v110, 0x3fb8aa3b, v122
	v_exp_f32_e32 v110, v110
	v_add_f32_e32 v111, v122, v122
	v_cmp_nlt_f32_e32 vcc, s75, v111
	s_and_saveexec_b64 s[6:7], vcc
	s_xor_b64 s[6:7], exec, s[6:7]
	v_fma_f32 v122, -v110, v110, 1.0
	s_andn2_saveexec_b64 s[6:7], s[6:7]
	v_fmamk_f32 v120, v111, 0x3c088889, v125
	v_fmaak_f32 v120, v111, v120, 0x3e2aaaab
	v_fma_f32 v120, v111, v120, 0.5
	v_fma_f32 v120, v111, v120, 1.0
	v_mul_f32_e64 v122, v120, -v111
	s_or_b64 exec, exec, s[6:7]
	v_mul_f32_e32 v111, 0x3fb8aa3b, v123
	v_exp_f32_e32 v111, v111
	v_add_f32_e32 v120, v123, v123
	v_cmp_nlt_f32_e32 vcc, s75, v120
	s_and_saveexec_b64 s[6:7], vcc
	s_xor_b64 s[6:7], exec, s[6:7]
	v_fma_f32 v123, -v111, v111, 1.0
	s_andn2_saveexec_b64 s[6:7], s[6:7]
	v_fmamk_f32 v123, v120, 0x3c088889, v125
	v_fmaak_f32 v123, v120, v123, 0x3e2aaaab
	v_fma_f32 v123, v120, v123, 0.5
	v_fma_f32 v123, v120, v123, 1.0
	v_mul_f32_e64 v123, v123, -v120
	s_or_b64 exec, exec, s[6:7]
	v_max_f32_e32 v3, v3, v3
	v_max_f32_e32 v3, 0, v3
	v_sqrt_f32_e32 v3, v3
	v_max_f32_e32 v121, v121, v121
	v_max_f32_e32 v121, 0, v121
	v_mov_b32_e32 v120, 0
	s_waitcnt lgkmcnt(1)
	v_mul_f32_e32 v3, v112, v3
	v_sqrt_f32_e32 v112, v121
	v_max_f32_e32 v121, v122, v122
	v_max_f32_e32 v121, 0, v121
	v_sqrt_f32_e32 v121, v121
	s_waitcnt lgkmcnt(0)
	v_mul_f32_e32 v116, v116, v3
	v_mul_f32_e32 v3, v113, v112
	v_mul_f32_e32 v117, v117, v3
	v_mul_f32_e32 v3, v114, v121
	v_mul_f32_e32 v118, v118, v3
	v_max_f32_e32 v3, v123, v123
	v_max_f32_e32 v3, 0, v3
	v_sqrt_f32_e32 v3, v3
	v_ashrrev_i32_e32 v114, 7, v0
	v_and_b32_e32 v121, 0x7f, v0
	v_bfe_u32 v113, v0, 6, 1
	v_mul_f32_e32 v3, v115, v3
	v_mul_f32_e32 v119, v119, v3
	ds_write_b128 v2, v[108:111] offset:25600
	ds_write_b128 v2, v[116:119] offset:58368
	v_lshlrev_b32_e32 v2, 4, v114
	v_or_b32_e32 v115, 2, v2
	v_and_b32_e32 v112, 63, v0
	v_cmp_gt_u32_e32 vcc, 64, v121
	v_sub_u32_e32 v116, 63, v115
	v_lshl_or_b32 v3, v113, 12, v112
	v_cndmask_b32_e32 v115, v116, v115, vcc
	v_lshl_add_u32 v115, v115, 6, v3
	v_lshl_add_u32 v115, v115, 2, 0
	s_waitcnt lgkmcnt(0)
	s_barrier
	ds_read2st64_b32 v[116:117], v115 offset0:100 offset1:228
	v_or_b32_e32 v115, 3, v2
	v_sub_u32_e32 v118, 63, v115
	v_cndmask_b32_e32 v115, v118, v115, vcc
	v_lshl_add_u32 v115, v115, 6, v3
	v_lshl_add_u32 v115, v115, 2, 0
	ds_read2st64_b32 v[118:119], v115 offset0:100 offset1:228
	v_or_b32_e32 v115, 4, v2
	v_sub_u32_e32 v122, 63, v115
	v_cndmask_b32_e32 v115, v122, v115, vcc
	v_lshl_add_u32 v115, v115, 6, v3
	v_lshl_add_u32 v115, v115, 2, 0
	ds_read2st64_b32 v[122:123], v115 offset0:100 offset1:228
	v_or_b32_e32 v115, 5, v2
	v_sub_u32_e32 v127, 63, v115
	v_cndmask_b32_e32 v115, v127, v115, vcc
	v_lshl_add_u32 v115, v115, 6, v3
	v_lshl_add_u32 v115, v115, 2, 0
	ds_read2st64_b32 v[128:129], v115 offset0:100 offset1:228
	v_or_b32_e32 v115, 6, v2
	v_sub_u32_e32 v127, 63, v115
	v_cndmask_b32_e32 v115, v127, v115, vcc
	v_lshl_add_u32 v115, v115, 6, v3
	v_lshl_add_u32 v115, v115, 2, 0
	ds_read2st64_b32 v[130:131], v115 offset0:100 offset1:228
	v_or_b32_e32 v115, 7, v2
	v_sub_u32_e32 v127, 63, v115
	v_cndmask_b32_e32 v115, v127, v115, vcc
	v_lshl_add_u32 v115, v115, 6, v3
	v_lshl_add_u32 v115, v115, 2, 0
	ds_read2st64_b32 v[132:133], v115 offset0:100 offset1:228
	v_or_b32_e32 v115, 8, v2
	v_sub_u32_e32 v127, 63, v115
	v_cndmask_b32_e32 v115, v127, v115, vcc
	v_lshl_add_u32 v115, v115, 6, v3
	v_lshl_add_u32 v115, v115, 2, 0
	ds_read2st64_b32 v[134:135], v115 offset0:100 offset1:228
	v_or_b32_e32 v115, 9, v2
	v_sub_u32_e32 v127, 63, v115
	v_cndmask_b32_e32 v115, v127, v115, vcc
	v_lshl_add_u32 v115, v115, 6, v3
	v_lshl_add_u32 v115, v115, 2, 0
	ds_read2st64_b32 v[136:137], v115 offset0:100 offset1:228
	v_or_b32_e32 v115, 10, v2
	v_sub_u32_e32 v127, 63, v115
	v_cndmask_b32_e32 v115, v127, v115, vcc
	v_lshl_add_u32 v115, v115, 6, v3
	v_lshl_add_u32 v115, v115, 2, 0
	ds_read2st64_b32 v[138:139], v115 offset0:100 offset1:228
	v_or_b32_e32 v115, 11, v2
	v_sub_u32_e32 v127, 63, v115
	v_cndmask_b32_e32 v115, v127, v115, vcc
	v_lshl_add_u32 v115, v115, 6, v3
	v_lshl_add_u32 v115, v115, 2, 0
	v_sub_u32_e32 v108, 63, v2
	v_or_b32_e32 v110, 1, v2
	ds_read2st64_b32 v[140:141], v115 offset0:100 offset1:228
	v_or_b32_e32 v115, 12, v2
	v_cndmask_b32_e32 v108, v108, v2, vcc
	v_sub_u32_e32 v111, 63, v110
	v_sub_u32_e32 v127, 63, v115
	v_lshl_add_u32 v108, v108, 6, v3
	v_cndmask_b32_e32 v110, v111, v110, vcc
	v_cndmask_b32_e32 v115, v127, v115, vcc
	v_lshl_add_u32 v108, v108, 2, 0
	v_lshl_add_u32 v110, v110, 6, v3
	v_lshl_add_u32 v115, v115, 6, v3
	ds_read2st64_b32 v[108:109], v108 offset0:100 offset1:228
	v_lshl_add_u32 v110, v110, 2, 0
	v_lshl_add_u32 v115, v115, 2, 0
	ds_read2st64_b32 v[110:111], v110 offset0:100 offset1:228
	ds_read2st64_b32 v[142:143], v115 offset0:100 offset1:228
	v_or_b32_e32 v115, 13, v2
	v_sub_u32_e32 v127, 63, v115
	v_cndmask_b32_e32 v115, v127, v115, vcc
	v_lshl_add_u32 v115, v115, 6, v3
	v_lshl_add_u32 v115, v115, 2, 0
	s_waitcnt lgkmcnt(2)
	v_fma_f32 v109, 0, v108, v109
	ds_read2st64_b32 v[144:145], v115 offset0:100 offset1:228
	v_or_b32_e32 v115, 14, v2
	s_waitcnt lgkmcnt(2)
	v_mul_f32_e32 v108, v108, v110
	v_fmac_f32_e32 v111, v109, v110
	v_sub_u32_e32 v127, 63, v115
	v_mul_f32_e32 v108, v108, v116
	v_fmac_f32_e32 v117, v111, v116
	v_cndmask_b32_e32 v115, v127, v115, vcc
	v_mul_f32_e32 v108, v108, v118
	v_fmac_f32_e32 v119, v117, v118
	v_lshl_add_u32 v115, v115, 6, v3
	v_mul_f32_e32 v108, v108, v122
	v_fmac_f32_e32 v123, v119, v122
	v_lshl_add_u32 v115, v115, 2, 0
	v_or_b32_e32 v2, 15, v2
	v_mul_f32_e32 v108, v108, v128
	v_fmac_f32_e32 v129, v123, v128
	ds_read2st64_b32 v[146:147], v115 offset0:100 offset1:228
	v_sub_u32_e32 v115, 63, v2
	v_mul_f32_e32 v108, v108, v130
	v_fmac_f32_e32 v131, v129, v130
	v_cndmask_b32_e32 v2, v115, v2, vcc
	v_mul_f32_e32 v108, v108, v132
	v_fmac_f32_e32 v133, v131, v132
	v_lshl_add_u32 v2, v2, 6, v3
	v_mul_f32_e32 v108, v108, v134
	v_fmac_f32_e32 v135, v133, v134
	v_lshl_add_u32 v2, v2, 2, 0
	v_mul_f32_e32 v108, v108, v136
	v_fmac_f32_e32 v137, v135, v136
	ds_read2st64_b32 v[2:3], v2 offset0:100 offset1:228
	v_mul_f32_e32 v108, v108, v138
	v_fmac_f32_e32 v139, v137, v138
	v_mul_f32_e32 v108, v108, v140
	v_fmac_f32_e32 v141, v139, v140
	s_waitcnt lgkmcnt(3)
	v_mul_f32_e32 v108, v108, v142
	v_fmac_f32_e32 v143, v141, v142
	s_waitcnt lgkmcnt(2)
	v_mul_f32_e32 v108, v108, v144
	v_fmac_f32_e32 v145, v143, v144
	s_waitcnt lgkmcnt(1)
	v_mul_f32_e32 v108, v108, v146
	v_fmac_f32_e32 v147, v145, v146
	v_lshl_add_u32 v0, v0, 2, 0
	s_waitcnt lgkmcnt(0)
	v_mul_f32_e32 v108, v108, v2
	v_fmac_f32_e32 v3, v147, v2
	v_add_u32_e32 v2, 0x16400, v0
	v_add_u32_e32 v0, 0x16c00, v0
	ds_write_b32 v2, v108
	ds_write_b32 v0, v3
	v_cmp_lt_i32_e32 vcc, 0, v114
	v_mov_b32_e32 v0, 1.0
	v_lshl_add_u32 v2, v121, 2, 0
	s_waitcnt vmcnt(0) lgkmcnt(0)
	s_barrier
	s_and_saveexec_b64 s[6:7], vcc
	s_cbranch_execnz .LBB0_434
	s_or_b64 exec, exec, s[6:7]
	v_cmp_lt_i32_e32 vcc, 1, v114
	s_and_saveexec_b64 s[6:7], vcc
	s_cbranch_execnz .LBB0_435
